# GEMM K-loop: first iteration after an epilogue peeled with vmcnt relaxed by the number of epilogue stores in phases 1-2, so MFMAs do not wait for store acks
# baseline (speedup 1.0000x reference)
.LBB0_215:
	s_ashr_i32 s43, s42, 31
	s_lshl_b64 s[28:29], s[42:43], 20
	s_add_u32 s44, s68, s28
	s_addc_u32 s45, s69, s29
	s_and_b64 s[28:29], s[38:39], exec
	s_cselect_b32 s43, s45, s51
	s_cselect_b32 s84, s44, s50
	s_ashr_i32 s41, s40, 31
	s_lshl_b64 s[28:29], s[40:41], 20
	v_readlane_b32 s41, v255, 6
	s_add_u32 s46, s41, s28
	v_readlane_b32 s28, v255, 7
	s_addc_u32 s47, s28, s29
	s_and_b64 s[28:29], s[38:39], exec
	s_cselect_b32 s41, s47, s53
	s_cselect_b32 s85, s46, s52
	s_add_u32 s50, s50, 0x80080
	s_addc_u32 s51, s51, 0
	s_add_u32 s86, s52, 0x100
	v_mov_b32_e32 v0, 0
	s_addc_u32 s87, s53, 0
	s_mov_b32 s88, -2
	v_mov_b32_e32 v1, v0
	v_mov_b32_e32 v2, v0
	v_mov_b32_e32 v3, v0
	v_mov_b32_e32 v4, v0
	v_mov_b32_e32 v5, v0
	v_mov_b32_e32 v6, v0
	v_mov_b32_e32 v7, v0
	v_mov_b32_e32 v8, v0
	v_mov_b32_e32 v9, v0
	v_mov_b32_e32 v10, v0
	v_mov_b32_e32 v11, v0
	v_mov_b32_e32 v18, v0
	v_mov_b32_e32 v19, v0
	v_mov_b32_e32 v20, v0
	v_mov_b32_e32 v21, v0
	v_mov_b32_e32 v26, v0
	v_mov_b32_e32 v27, v0
	v_mov_b32_e32 v28, v0
	v_mov_b32_e32 v29, v0
	v_mov_b32_e32 v34, v0
	v_mov_b32_e32 v35, v0
	v_mov_b32_e32 v36, v0
	v_mov_b32_e32 v37, v0
	v_mov_b32_e32 v42, v0
	v_mov_b32_e32 v43, v0
	v_mov_b32_e32 v44, v0
	v_mov_b32_e32 v45, v0
	v_mov_b32_e32 v50, v0
	v_mov_b32_e32 v51, v0
	v_mov_b32_e32 v52, v0
	v_mov_b32_e32 v53, v0
	v_mov_b32_e32 v12, v0
	v_mov_b32_e32 v13, v0
	v_mov_b32_e32 v14, v0
	v_mov_b32_e32 v15, v0
	v_mov_b32_e32 v22, v0
	v_mov_b32_e32 v23, v0
	v_mov_b32_e32 v24, v0
	v_mov_b32_e32 v25, v0
	v_mov_b32_e32 v30, v0
	v_mov_b32_e32 v31, v0
	v_mov_b32_e32 v32, v0
	v_mov_b32_e32 v33, v0
	v_mov_b32_e32 v38, v0
	v_mov_b32_e32 v39, v0
	v_mov_b32_e32 v40, v0
	v_mov_b32_e32 v41, v0
	v_mov_b32_e32 v46, v0
	v_mov_b32_e32 v47, v0
	v_mov_b32_e32 v48, v0
	v_mov_b32_e32 v49, v0
	v_mov_b32_e32 v54, v0
	v_mov_b32_e32 v55, v0
	v_mov_b32_e32 v56, v0
	v_mov_b32_e32 v57, v0
	v_mov_b32_e32 v58, v0
	v_mov_b32_e32 v59, v0
	v_mov_b32_e32 v60, v0
	v_mov_b32_e32 v61, v0
	v_mov_b32_e32 v62, v0
	v_mov_b32_e32 v63, v0
	v_mov_b32_e32 v64, v0
	v_mov_b32_e32 v65, v0
	v_mov_b32_e32 v66, v0
	v_mov_b32_e32 v67, v0
	v_mov_b32_e32 v68, v0
	v_mov_b32_e32 v69, v0
	v_mov_b32_e32 v70, v0
	v_mov_b32_e32 v71, v0
	v_mov_b32_e32 v72, v0
	v_mov_b32_e32 v73, v0
	v_mov_b32_e32 v74, v0
	v_mov_b32_e32 v75, v0
	v_mov_b32_e32 v76, v0
	v_mov_b32_e32 v77, v0
	v_mov_b32_e32 v82, v0
	v_mov_b32_e32 v83, v0
	v_mov_b32_e32 v84, v0
	v_mov_b32_e32 v85, v0
	v_mov_b32_e32 v90, v0
	v_mov_b32_e32 v91, v0
	v_mov_b32_e32 v92, v0
	v_mov_b32_e32 v93, v0
	v_mov_b32_e32 v98, v0
	v_mov_b32_e32 v99, v0
	v_mov_b32_e32 v100, v0
	v_mov_b32_e32 v101, v0
	v_mov_b32_e32 v106, v0
	v_mov_b32_e32 v107, v0
	v_mov_b32_e32 v108, v0
	v_mov_b32_e32 v109, v0
	v_mov_b32_e32 v114, v0
	v_mov_b32_e32 v115, v0
	v_mov_b32_e32 v116, v0
	v_mov_b32_e32 v117, v0
	v_mov_b32_e32 v78, v0
	v_mov_b32_e32 v79, v0
	v_mov_b32_e32 v80, v0
	v_mov_b32_e32 v81, v0
	v_mov_b32_e32 v86, v0
	v_mov_b32_e32 v87, v0
	v_mov_b32_e32 v88, v0
	v_mov_b32_e32 v89, v0
	v_mov_b32_e32 v94, v0
	v_mov_b32_e32 v95, v0
	v_mov_b32_e32 v96, v0
	v_mov_b32_e32 v97, v0
	v_mov_b32_e32 v102, v0
	v_mov_b32_e32 v103, v0
	v_mov_b32_e32 v104, v0
	v_mov_b32_e32 v105, v0
	v_mov_b32_e32 v110, v0
	v_mov_b32_e32 v111, v0
	v_mov_b32_e32 v112, v0
	v_mov_b32_e32 v113, v0
	v_mov_b32_e32 v118, v0
	v_mov_b32_e32 v119, v0
	v_mov_b32_e32 v120, v0
	v_mov_b32_e32 v121, v0
	v_mov_b32_e32 v122, v0
	v_mov_b32_e32 v123, v0
	v_mov_b32_e32 v124, v0
	v_mov_b32_e32 v125, v0
	v_mov_b32_e32 v126, v0
	v_mov_b32_e32 v127, v0
	v_mov_b32_e32 v128, v0
	v_mov_b32_e32 v129, v0
	s_cmp_eq_u32 s59, 1
	s_cbranch_scc1 .LBB0_216
	s_add_u32 s28, s50, 0xfff80080
	s_addc_u32 s29, s51, -1
	s_add_i32 s89, 0, 0x10000
	s_cmp_eq_u32 s88, 28
	s_cselect_b32 s53, s43, s29
	s_cselect_b32 s52, s84, s28
	s_cselect_b32 s29, s41, s87
	s_cselect_b32 s28, s85, s86
	s_add_i32 s92, 0, 0x14000
	v_add_u32_e32 v158, s89, v147
	v_add_u32_e32 v174, s92, v147
	ds_read_b128 v[142:145], v158
	ds_read_b128 v[150:153], v158 offset:1024
	ds_read_b128 v[154:157], v158 offset:2048
	ds_read_b128 v[158:161], v158 offset:3072
	ds_read_b128 v[162:165], v174
	ds_read_b128 v[166:169], v174 offset:1024
	ds_read_b128 v[170:173], v174 offset:2048
	ds_read_b128 v[174:177], v174 offset:3072
	v_lshl_add_u64 v[206:207], s[50:51], 0, v[138:139]
	s_add_i32 m0, s36, 0xc000
	ds_read_b128 v[178:181], v149
	ds_read_b128 v[182:185], v149 offset:1024
	ds_read_b128 v[186:189], v149 offset:2048
	ds_read_b128 v[190:193], v149 offset:3072
	ds_read_b128 v[194:197], v149 offset:4096
	ds_read_b128 v[198:201], v149 offset:5120
	ds_read_b128 v[202:205], v149 offset:6144
	ds_read_b128 v[224:227], v149 offset:7168
	global_load_lds_dwordx4 v[206:207], off
	v_lshl_add_u64 v[206:207], s[50:51], 0, v[140:141]
	s_add_i32 m0, s36, 0xe000
	s_nop 0
	global_load_lds_dwordx4 v[206:207], off
	s_waitcnt vmcnt(24)
	s_waitcnt lgkmcnt(0)
	s_barrier
	s_setprio 1
	s_waitcnt lgkmcnt(0)
	v_mfma_f32_16x16x32_bf16 v[126:129], v[142:145], v[178:181], v[126:129]
	v_mfma_f32_16x16x32_bf16 v[122:125], v[154:157], v[178:181], v[122:125]
	v_mfma_f32_16x16x32_bf16 v[118:121], v[142:145], v[186:189], v[118:121]
	v_mfma_f32_16x16x32_bf16 v[110:113], v[154:157], v[186:189], v[110:113]
	v_mfma_f32_16x16x32_bf16 v[102:105], v[142:145], v[194:197], v[102:105]
	v_mfma_f32_16x16x32_bf16 v[94:97], v[154:157], v[194:197], v[94:97]
	v_mfma_f32_16x16x32_bf16 v[86:89], v[142:145], v[202:205], v[86:89]
	v_mfma_f32_16x16x32_bf16 v[78:81], v[154:157], v[202:205], v[78:81]
	v_mfma_f32_16x16x32_bf16 v[126:129], v[150:153], v[182:185], v[126:129]
	v_mfma_f32_16x16x32_bf16 v[122:125], v[158:161], v[182:185], v[122:125]
	v_mfma_f32_16x16x32_bf16 v[118:121], v[150:153], v[190:193], v[118:121]
	v_mfma_f32_16x16x32_bf16 v[110:113], v[158:161], v[190:193], v[110:113]
	v_mfma_f32_16x16x32_bf16 v[102:105], v[150:153], v[198:201], v[102:105]
	v_mfma_f32_16x16x32_bf16 v[94:97], v[158:161], v[198:201], v[94:97]
	v_mfma_f32_16x16x32_bf16 v[86:89], v[150:153], v[224:227], v[86:89]
	v_mfma_f32_16x16x32_bf16 v[78:81], v[158:161], v[224:227], v[78:81]
	s_setprio 0
	s_setprio 1
	v_mfma_f32_16x16x32_bf16 v[114:117], v[162:165], v[178:181], v[114:117]
	v_mfma_f32_16x16x32_bf16 v[106:109], v[170:173], v[178:181], v[106:109]
	v_mfma_f32_16x16x32_bf16 v[98:101], v[162:165], v[186:189], v[98:101]
	v_mfma_f32_16x16x32_bf16 v[90:93], v[170:173], v[186:189], v[90:93]
	v_mfma_f32_16x16x32_bf16 v[82:85], v[162:165], v[194:197], v[82:85]
	v_mfma_f32_16x16x32_bf16 v[74:77], v[170:173], v[194:197], v[74:77]
	v_mfma_f32_16x16x32_bf16 v[70:73], v[162:165], v[202:205], v[70:73]
	v_mfma_f32_16x16x32_bf16 v[66:69], v[170:173], v[202:205], v[66:69]
	v_mfma_f32_16x16x32_bf16 v[114:117], v[166:169], v[182:185], v[114:117]
	v_mfma_f32_16x16x32_bf16 v[106:109], v[174:177], v[182:185], v[106:109]
	v_mfma_f32_16x16x32_bf16 v[98:101], v[166:169], v[190:193], v[98:101]
	v_mfma_f32_16x16x32_bf16 v[90:93], v[174:177], v[190:193], v[90:93]
	v_mfma_f32_16x16x32_bf16 v[82:85], v[166:169], v[198:201], v[82:85]
	v_mfma_f32_16x16x32_bf16 v[74:77], v[174:177], v[198:201], v[74:77]
	v_mfma_f32_16x16x32_bf16 v[70:73], v[166:169], v[224:227], v[70:73]
	v_mfma_f32_16x16x32_bf16 v[66:69], v[174:177], v[224:227], v[66:69]
	s_setprio 0
	s_barrier
	s_add_i32 s89, s89, s26
	v_lshl_add_u64 v[206:207], s[28:29], 0, v[134:135]
	s_mov_b32 m0, s89
	ds_read_b128 v[178:181], v149 offset:16384
	ds_read_b128 v[182:185], v149 offset:17408
	ds_read_b128 v[186:189], v149 offset:18432
	ds_read_b128 v[190:193], v149 offset:19456
	ds_read_b128 v[194:197], v149 offset:20480
	ds_read_b128 v[198:201], v149 offset:21504
	ds_read_b128 v[202:205], v149 offset:22528
	ds_read_b128 v[224:227], v149 offset:23552
	global_load_lds_dwordx4 v[206:207], off
	s_add_i32 m0, s89, 0x2000
	s_add_u32 s90, s28, 0x80000
	v_lshl_add_u64 v[228:229], s[28:29], 0, v[130:131]
	s_addc_u32 s91, s29, 0
	s_add_i32 s89, s92, s26
	global_load_lds_dwordx4 v[228:229], off
	v_lshl_add_u64 v[230:231], s[90:91], 0, v[134:135]
	s_mov_b32 m0, s89
	v_lshl_add_u64 v[232:233], s[52:53], 0, v[132:133]
	global_load_lds_dwordx4 v[230:231], off
	v_lshl_add_u64 v[230:231], s[90:91], 0, v[130:131]
	s_add_i32 m0, s89, 0x2000
	s_nop 0
	global_load_lds_dwordx4 v[230:231], off
	v_lshl_add_u64 v[230:231], s[52:53], 0, v[136:137]
	s_mov_b32 m0, s36
	s_nop 0
	global_load_lds_dwordx4 v[230:231], off
	s_mov_b32 m0, s37
	s_nop 0
	global_load_lds_dwordx4 v[232:233], off
	s_waitcnt vmcnt(24)
	s_waitcnt lgkmcnt(0)
	s_barrier
	s_setprio 1
	s_waitcnt lgkmcnt(0)
	v_mfma_f32_16x16x32_bf16 v[62:65], v[142:145], v[178:181], v[62:65]
	v_mfma_f32_16x16x32_bf16 v[58:61], v[154:157], v[178:181], v[58:61]
	v_mfma_f32_16x16x32_bf16 v[54:57], v[142:145], v[186:189], v[54:57]
	v_mfma_f32_16x16x32_bf16 v[46:49], v[154:157], v[186:189], v[46:49]
	v_mfma_f32_16x16x32_bf16 v[38:41], v[142:145], v[194:197], v[38:41]
	v_mfma_f32_16x16x32_bf16 v[30:33], v[154:157], v[194:197], v[30:33]
	v_mfma_f32_16x16x32_bf16 v[22:25], v[142:145], v[202:205], v[22:25]
	v_mfma_f32_16x16x32_bf16 v[12:15], v[154:157], v[202:205], v[12:15]
	v_mfma_f32_16x16x32_bf16 v[62:65], v[150:153], v[182:185], v[62:65]
	v_mfma_f32_16x16x32_bf16 v[58:61], v[158:161], v[182:185], v[58:61]
	v_mfma_f32_16x16x32_bf16 v[54:57], v[150:153], v[190:193], v[54:57]
	v_mfma_f32_16x16x32_bf16 v[46:49], v[158:161], v[190:193], v[46:49]
	v_mfma_f32_16x16x32_bf16 v[38:41], v[150:153], v[198:201], v[38:41]
	v_mfma_f32_16x16x32_bf16 v[30:33], v[158:161], v[198:201], v[30:33]
	v_mfma_f32_16x16x32_bf16 v[22:25], v[150:153], v[224:227], v[22:25]
	v_mfma_f32_16x16x32_bf16 v[12:15], v[158:161], v[224:227], v[12:15]
	s_setprio 0
	s_setprio 1
	v_mfma_f32_16x16x32_bf16 v[50:53], v[162:165], v[178:181], v[50:53]
	v_mfma_f32_16x16x32_bf16 v[42:45], v[170:173], v[178:181], v[42:45]
	v_mfma_f32_16x16x32_bf16 v[34:37], v[162:165], v[186:189], v[34:37]
	v_mfma_f32_16x16x32_bf16 v[26:29], v[170:173], v[186:189], v[26:29]
	v_mfma_f32_16x16x32_bf16 v[18:21], v[162:165], v[194:197], v[18:21]
	v_mfma_f32_16x16x32_bf16 v[8:11], v[170:173], v[194:197], v[8:11]
	v_mfma_f32_16x16x32_bf16 v[4:7], v[162:165], v[202:205], v[4:7]
	v_mfma_f32_16x16x32_bf16 v[0:3], v[170:173], v[202:205], v[0:3]
	v_mfma_f32_16x16x32_bf16 v[50:53], v[166:169], v[182:185], v[50:53]
	v_mfma_f32_16x16x32_bf16 v[42:45], v[174:177], v[182:185], v[42:45]
	v_mfma_f32_16x16x32_bf16 v[34:37], v[166:169], v[190:193], v[34:37]
	v_mfma_f32_16x16x32_bf16 v[26:29], v[174:177], v[190:193], v[26:29]
	v_mfma_f32_16x16x32_bf16 v[18:21], v[166:169], v[198:201], v[18:21]
	v_mfma_f32_16x16x32_bf16 v[8:11], v[174:177], v[198:201], v[8:11]
	v_mfma_f32_16x16x32_bf16 v[4:7], v[166:169], v[224:227], v[4:7]
	v_mfma_f32_16x16x32_bf16 v[0:3], v[174:177], v[224:227], v[0:3]
	s_setprio 0
	s_barrier
	s_add_i32 s89, 0, 0x18000
	s_add_i32 s90, 0, 0x1c000
	v_add_u32_e32 v158, s89, v147
	v_add_u32_e32 v174, s90, v147
	ds_read_b128 v[142:145], v158
	ds_read_b128 v[150:153], v158 offset:1024
	ds_read_b128 v[154:157], v158 offset:2048
	ds_read_b128 v[158:161], v158 offset:3072
	ds_read_b128 v[162:165], v174
	ds_read_b128 v[166:169], v174 offset:1024
	ds_read_b128 v[170:173], v174 offset:2048
	ds_read_b128 v[174:177], v174 offset:3072
	s_add_u32 s52, s52, 0x80000
	s_addc_u32 s53, s53, 0
	s_mov_b32 m0, s49
	v_lshl_add_u64 v[234:235], s[52:53], 0, v[136:137]
	ds_read_b128 v[178:181], v149 offset:32768
	ds_read_b128 v[182:185], v149 offset:33792
	ds_read_b128 v[186:189], v149 offset:34816
	ds_read_b128 v[190:193], v149 offset:35840
	ds_read_b128 v[194:197], v149 offset:36864
	ds_read_b128 v[198:201], v149 offset:37888
	ds_read_b128 v[202:205], v149 offset:38912
	ds_read_b128 v[224:227], v149 offset:39936
	global_load_lds_dwordx4 v[234:235], off
	v_lshl_add_u64 v[234:235], s[52:53], 0, v[132:133]
	s_mov_b32 m0, s56
	s_nop 0
	global_load_lds_dwordx4 v[234:235], off
	s_waitcnt vmcnt(8)
	s_waitcnt lgkmcnt(0)
	s_barrier
	s_setprio 1
	s_waitcnt lgkmcnt(0)
	v_mfma_f32_16x16x32_bf16 v[126:129], v[142:145], v[178:181], v[126:129]
	v_mfma_f32_16x16x32_bf16 v[122:125], v[154:157], v[178:181], v[122:125]
	v_mfma_f32_16x16x32_bf16 v[118:121], v[142:145], v[186:189], v[118:121]
	v_mfma_f32_16x16x32_bf16 v[110:113], v[154:157], v[186:189], v[110:113]
	v_mfma_f32_16x16x32_bf16 v[102:105], v[142:145], v[194:197], v[102:105]
	v_mfma_f32_16x16x32_bf16 v[94:97], v[154:157], v[194:197], v[94:97]
	v_mfma_f32_16x16x32_bf16 v[86:89], v[142:145], v[202:205], v[86:89]
	v_mfma_f32_16x16x32_bf16 v[78:81], v[154:157], v[202:205], v[78:81]
	v_mfma_f32_16x16x32_bf16 v[126:129], v[150:153], v[182:185], v[126:129]
	v_mfma_f32_16x16x32_bf16 v[122:125], v[158:161], v[182:185], v[122:125]
	v_mfma_f32_16x16x32_bf16 v[118:121], v[150:153], v[190:193], v[118:121]
	v_mfma_f32_16x16x32_bf16 v[110:113], v[158:161], v[190:193], v[110:113]
	v_mfma_f32_16x16x32_bf16 v[102:105], v[150:153], v[198:201], v[102:105]
	v_mfma_f32_16x16x32_bf16 v[94:97], v[158:161], v[198:201], v[94:97]
	v_mfma_f32_16x16x32_bf16 v[86:89], v[150:153], v[224:227], v[86:89]
	v_mfma_f32_16x16x32_bf16 v[78:81], v[158:161], v[224:227], v[78:81]
	s_setprio 0
	s_setprio 1
	v_mfma_f32_16x16x32_bf16 v[114:117], v[162:165], v[178:181], v[114:117]
	v_mfma_f32_16x16x32_bf16 v[106:109], v[170:173], v[178:181], v[106:109]
	v_mfma_f32_16x16x32_bf16 v[98:101], v[162:165], v[186:189], v[98:101]
	v_mfma_f32_16x16x32_bf16 v[90:93], v[170:173], v[186:189], v[90:93]
	v_mfma_f32_16x16x32_bf16 v[82:85], v[162:165], v[194:197], v[82:85]
	v_mfma_f32_16x16x32_bf16 v[74:77], v[170:173], v[194:197], v[74:77]
	v_mfma_f32_16x16x32_bf16 v[70:73], v[162:165], v[202:205], v[70:73]
	v_mfma_f32_16x16x32_bf16 v[66:69], v[170:173], v[202:205], v[66:69]
	v_mfma_f32_16x16x32_bf16 v[114:117], v[166:169], v[182:185], v[114:117]
	v_mfma_f32_16x16x32_bf16 v[106:109], v[174:177], v[182:185], v[106:109]
	v_mfma_f32_16x16x32_bf16 v[98:101], v[166:169], v[190:193], v[98:101]
	v_mfma_f32_16x16x32_bf16 v[90:93], v[174:177], v[190:193], v[90:93]
	v_mfma_f32_16x16x32_bf16 v[82:85], v[166:169], v[198:201], v[82:85]
	v_mfma_f32_16x16x32_bf16 v[74:77], v[174:177], v[198:201], v[74:77]
	v_mfma_f32_16x16x32_bf16 v[70:73], v[166:169], v[224:227], v[70:73]
	v_mfma_f32_16x16x32_bf16 v[66:69], v[174:177], v[224:227], v[66:69]
	s_setprio 0
	s_barrier
	s_add_i32 s52, s89, s26
	v_lshl_add_u64 v[206:207], v[206:207], 0, s[34:35]
	s_mov_b32 m0, s52
	ds_read_b128 v[178:181], v149 offset:49152
	ds_read_b128 v[182:185], v149 offset:50176
	ds_read_b128 v[186:189], v149 offset:51200
	ds_read_b128 v[190:193], v149 offset:52224
	ds_read_b128 v[194:197], v149 offset:53248
	ds_read_b128 v[198:201], v149 offset:54272
	ds_read_b128 v[202:205], v149 offset:55296
	ds_read_b128 v[224:227], v149 offset:56320
	global_load_lds_dwordx4 v[206:207], off
	s_add_i32 m0, s52, 0x2000
	s_add_u32 s28, s28, 0x80080
	v_lshl_add_u64 v[206:207], v[228:229], 0, s[34:35]
	s_addc_u32 s29, s29, 0
	s_add_i32 s52, s90, s26
	global_load_lds_dwordx4 v[206:207], off
	v_lshl_add_u64 v[206:207], s[28:29], 0, v[134:135]
	s_mov_b32 m0, s52
	s_nop 0
	global_load_lds_dwordx4 v[206:207], off
	v_lshl_add_u64 v[206:207], s[28:29], 0, v[130:131]
	s_add_i32 m0, s52, 0x2000
	s_nop 0
	global_load_lds_dwordx4 v[206:207], off
	v_lshl_add_u64 v[206:207], v[230:231], 0, s[34:35]
	s_mov_b32 m0, s57
	s_nop 0
	global_load_lds_dwordx4 v[206:207], off
	v_lshl_add_u64 v[206:207], v[232:233], 0, s[34:35]
	s_mov_b32 m0, s58
	s_nop 0
	global_load_lds_dwordx4 v[206:207], off
	s_waitcnt vmcnt(8)
	s_waitcnt lgkmcnt(0)
	s_barrier
	s_setprio 1
	s_waitcnt lgkmcnt(0)
	v_mfma_f32_16x16x32_bf16 v[62:65], v[142:145], v[178:181], v[62:65]
	v_mfma_f32_16x16x32_bf16 v[58:61], v[154:157], v[178:181], v[58:61]
	v_mfma_f32_16x16x32_bf16 v[54:57], v[142:145], v[186:189], v[54:57]
	v_mfma_f32_16x16x32_bf16 v[46:49], v[154:157], v[186:189], v[46:49]
	v_mfma_f32_16x16x32_bf16 v[38:41], v[142:145], v[194:197], v[38:41]
	v_mfma_f32_16x16x32_bf16 v[30:33], v[154:157], v[194:197], v[30:33]
	v_mfma_f32_16x16x32_bf16 v[22:25], v[142:145], v[202:205], v[22:25]
	v_mfma_f32_16x16x32_bf16 v[12:15], v[154:157], v[202:205], v[12:15]
	v_mfma_f32_16x16x32_bf16 v[62:65], v[150:153], v[182:185], v[62:65]
	v_mfma_f32_16x16x32_bf16 v[58:61], v[158:161], v[182:185], v[58:61]
	v_mfma_f32_16x16x32_bf16 v[54:57], v[150:153], v[190:193], v[54:57]
	v_mfma_f32_16x16x32_bf16 v[46:49], v[158:161], v[190:193], v[46:49]
	v_mfma_f32_16x16x32_bf16 v[38:41], v[150:153], v[198:201], v[38:41]
	v_mfma_f32_16x16x32_bf16 v[30:33], v[158:161], v[198:201], v[30:33]
	v_mfma_f32_16x16x32_bf16 v[22:25], v[150:153], v[224:227], v[22:25]
	v_mfma_f32_16x16x32_bf16 v[12:15], v[158:161], v[224:227], v[12:15]
	s_setprio 0
	s_setprio 1
	v_mfma_f32_16x16x32_bf16 v[50:53], v[162:165], v[178:181], v[50:53]
	v_mfma_f32_16x16x32_bf16 v[42:45], v[170:173], v[178:181], v[42:45]
	v_mfma_f32_16x16x32_bf16 v[34:37], v[162:165], v[186:189], v[34:37]
	v_mfma_f32_16x16x32_bf16 v[26:29], v[170:173], v[186:189], v[26:29]
	v_mfma_f32_16x16x32_bf16 v[18:21], v[162:165], v[194:197], v[18:21]
	v_mfma_f32_16x16x32_bf16 v[8:11], v[170:173], v[194:197], v[8:11]
	v_mfma_f32_16x16x32_bf16 v[4:7], v[162:165], v[202:205], v[4:7]
	v_mfma_f32_16x16x32_bf16 v[0:3], v[170:173], v[202:205], v[0:3]
	v_mfma_f32_16x16x32_bf16 v[50:53], v[166:169], v[182:185], v[50:53]
	v_mfma_f32_16x16x32_bf16 v[42:45], v[174:177], v[182:185], v[42:45]
	v_mfma_f32_16x16x32_bf16 v[34:37], v[166:169], v[190:193], v[34:37]
	v_mfma_f32_16x16x32_bf16 v[26:29], v[174:177], v[190:193], v[26:29]
	v_mfma_f32_16x16x32_bf16 v[18:21], v[166:169], v[198:201], v[18:21]
	v_mfma_f32_16x16x32_bf16 v[8:11], v[174:177], v[198:201], v[8:11]
	v_mfma_f32_16x16x32_bf16 v[4:7], v[166:169], v[224:227], v[4:7]
	v_mfma_f32_16x16x32_bf16 v[0:3], v[174:177], v[224:227], v[0:3]
	s_setprio 0
	s_barrier
	s_add_i32 s88, s88, 2
	s_add_u32 s50, s50, 0x100
	s_addc_u32 s51, s51, 0
	s_add_u32 s86, s86, 0x100
	s_addc_u32 s87, s87, 0
	s_cmp_gt_u32 s88, 29
	s_cbranch_scc1 .Lpk_B_exit

.Lpk_B_exit:
	s_and_b64 vcc, exec, s[18:19]
	s_cbranch_vccz .LBB0_221
	s_barrier
	s_cmp_gt_i32 s83, 13
	s_mov_b64 s[28:29], -1
	s_cbranch_scc1 .LBB0_222

.LBB0_648:
	s_ashr_i32 s19, s18, 31
	s_lshl_b64 s[28:29], s[18:19], 18
	v_readlane_b32 s19, v255, 10
	s_add_u32 s42, s19, s28
	v_readlane_b32 s19, v255, 11
	s_addc_u32 s43, s19, s29
	s_and_b64 s[28:29], s[40:41], exec
	s_cselect_b32 s19, s43, s47
	s_cselect_b32 s23, s42, s46
	s_add_u32 s40, s48, 0x80080
	s_addc_u32 s41, s49, 0
	s_add_u32 s48, s46, 0x100
	v_mov_b32_e32 v0, 0
	s_addc_u32 s49, s47, 0
	s_mov_b32 s87, -2
	v_mov_b32_e32 v1, v0
	v_mov_b32_e32 v2, v0
	v_mov_b32_e32 v3, v0
	v_mov_b32_e32 v4, v0
	v_mov_b32_e32 v5, v0
	v_mov_b32_e32 v6, v0
	v_mov_b32_e32 v7, v0
	v_mov_b32_e32 v8, v0
	v_mov_b32_e32 v9, v0
	v_mov_b32_e32 v10, v0
	v_mov_b32_e32 v11, v0
	v_mov_b32_e32 v18, v0
	v_mov_b32_e32 v19, v0
	v_mov_b32_e32 v20, v0
	v_mov_b32_e32 v21, v0
	v_mov_b32_e32 v26, v0
	v_mov_b32_e32 v27, v0
	v_mov_b32_e32 v28, v0
	v_mov_b32_e32 v29, v0
	v_mov_b32_e32 v34, v0
	v_mov_b32_e32 v35, v0
	v_mov_b32_e32 v36, v0
	v_mov_b32_e32 v37, v0
	v_mov_b32_e32 v42, v0
	v_mov_b32_e32 v43, v0
	v_mov_b32_e32 v44, v0
	v_mov_b32_e32 v45, v0
	v_mov_b32_e32 v50, v0
	v_mov_b32_e32 v51, v0
	v_mov_b32_e32 v52, v0
	v_mov_b32_e32 v53, v0
	v_mov_b32_e32 v12, v0
	v_mov_b32_e32 v13, v0
	v_mov_b32_e32 v14, v0
	v_mov_b32_e32 v15, v0
	v_mov_b32_e32 v22, v0
	v_mov_b32_e32 v23, v0
	v_mov_b32_e32 v24, v0
	v_mov_b32_e32 v25, v0
	v_mov_b32_e32 v30, v0
	v_mov_b32_e32 v31, v0
	v_mov_b32_e32 v32, v0
	v_mov_b32_e32 v33, v0
	v_mov_b32_e32 v38, v0
	v_mov_b32_e32 v39, v0
	v_mov_b32_e32 v40, v0
	v_mov_b32_e32 v41, v0
	v_mov_b32_e32 v46, v0
	v_mov_b32_e32 v47, v0
	v_mov_b32_e32 v48, v0
	v_mov_b32_e32 v49, v0
	v_mov_b32_e32 v54, v0
	v_mov_b32_e32 v55, v0
	v_mov_b32_e32 v56, v0
	v_mov_b32_e32 v57, v0
	v_mov_b32_e32 v58, v0
	v_mov_b32_e32 v59, v0
	v_mov_b32_e32 v60, v0
	v_mov_b32_e32 v61, v0
	v_mov_b32_e32 v62, v0
	v_mov_b32_e32 v63, v0
	v_mov_b32_e32 v64, v0
	v_mov_b32_e32 v65, v0
	v_mov_b32_e32 v66, v0
	v_mov_b32_e32 v67, v0
	v_mov_b32_e32 v68, v0
	v_mov_b32_e32 v69, v0
	v_mov_b32_e32 v70, v0
	v_mov_b32_e32 v71, v0
	v_mov_b32_e32 v72, v0
	v_mov_b32_e32 v73, v0
	v_mov_b32_e32 v74, v0
	v_mov_b32_e32 v75, v0
	v_mov_b32_e32 v76, v0
	v_mov_b32_e32 v77, v0
	v_mov_b32_e32 v82, v0
	v_mov_b32_e32 v83, v0
	v_mov_b32_e32 v84, v0
	v_mov_b32_e32 v85, v0
	v_mov_b32_e32 v90, v0
	v_mov_b32_e32 v91, v0
	v_mov_b32_e32 v92, v0
	v_mov_b32_e32 v93, v0
	v_mov_b32_e32 v98, v0
	v_mov_b32_e32 v99, v0
	v_mov_b32_e32 v100, v0
	v_mov_b32_e32 v101, v0
	v_mov_b32_e32 v106, v0
	v_mov_b32_e32 v107, v0
	v_mov_b32_e32 v108, v0
	v_mov_b32_e32 v109, v0
	v_mov_b32_e32 v114, v0
	v_mov_b32_e32 v115, v0
	v_mov_b32_e32 v116, v0
	v_mov_b32_e32 v117, v0
	v_mov_b32_e32 v78, v0
	v_mov_b32_e32 v79, v0
	v_mov_b32_e32 v80, v0
	v_mov_b32_e32 v81, v0
	v_mov_b32_e32 v86, v0
	v_mov_b32_e32 v87, v0
	v_mov_b32_e32 v88, v0
	v_mov_b32_e32 v89, v0
	v_mov_b32_e32 v94, v0
	v_mov_b32_e32 v95, v0
	v_mov_b32_e32 v96, v0
	v_mov_b32_e32 v97, v0
	v_mov_b32_e32 v102, v0
	v_mov_b32_e32 v103, v0
	v_mov_b32_e32 v104, v0
	v_mov_b32_e32 v105, v0
	v_mov_b32_e32 v110, v0
	v_mov_b32_e32 v111, v0
	v_mov_b32_e32 v112, v0
	v_mov_b32_e32 v113, v0
	v_mov_b32_e32 v118, v0
	v_mov_b32_e32 v119, v0
	v_mov_b32_e32 v120, v0
	v_mov_b32_e32 v121, v0
	v_mov_b32_e32 v122, v0
	v_mov_b32_e32 v123, v0
	v_mov_b32_e32 v124, v0
	v_mov_b32_e32 v125, v0
	v_mov_b32_e32 v126, v0
	v_mov_b32_e32 v127, v0
	v_mov_b32_e32 v128, v0
	v_mov_b32_e32 v129, v0
	s_cmp_eq_u32 s85, 1
	s_cbranch_scc1 .LBB0_649
	s_add_u32 s28, s40, 0xfff80080
	s_addc_u32 s29, s41, -1
	s_add_i32 s88, 0, 0x10000
	s_cmp_eq_u32 s87, 4
	s_cselect_b32 s47, s27, s29
	s_cselect_b32 s46, s26, s28
	v_add_u32_e32 v140, s88, v143
	s_cselect_b32 s29, s19, s49
	s_cselect_b32 s28, s23, s48
	s_add_i32 s90, 0, 0x14000
	ds_read_b128 v[146:149], v140
	ds_read_b128 v[150:153], v140 offset:1024
	ds_read_b128 v[154:157], v140 offset:2048
	ds_read_b128 v[158:161], v140 offset:3072
	v_add_u32_e32 v140, s90, v143
	ds_read_b128 v[162:165], v140
	ds_read_b128 v[166:169], v140 offset:1024
	ds_read_b128 v[170:173], v140 offset:2048
	ds_read_b128 v[174:177], v140 offset:3072
	v_lshl_add_u64 v[140:141], s[40:41], 0, v[136:137]
	s_add_i32 m0, s45, 0xc000
	ds_read_b128 v[178:181], v145
	ds_read_b128 v[182:185], v145 offset:1024
	ds_read_b128 v[186:189], v145 offset:2048
	ds_read_b128 v[190:193], v145 offset:3072
	ds_read_b128 v[194:197], v145 offset:4096
	ds_read_b128 v[198:201], v145 offset:5120
	ds_read_b128 v[202:205], v145 offset:6144
	ds_read_b128 v[224:227], v145 offset:7168
	global_load_lds_dwordx4 v[140:141], off
	v_lshl_add_u64 v[140:141], s[40:41], 0, v[138:139]
	s_add_i32 m0, s45, 0xe000
	s_nop 0
	global_load_lds_dwordx4 v[140:141], off
	s_waitcnt vmcnt(24)
	s_waitcnt lgkmcnt(0)
	s_barrier
	s_setprio 1
	s_waitcnt lgkmcnt(0)
	v_mfma_f32_16x16x32_bf16 v[126:129], v[146:149], v[178:181], v[126:129]
	v_mfma_f32_16x16x32_bf16 v[122:125], v[154:157], v[178:181], v[122:125]
	v_mfma_f32_16x16x32_bf16 v[118:121], v[146:149], v[186:189], v[118:121]
	v_mfma_f32_16x16x32_bf16 v[110:113], v[154:157], v[186:189], v[110:113]
	v_mfma_f32_16x16x32_bf16 v[102:105], v[146:149], v[194:197], v[102:105]
	v_mfma_f32_16x16x32_bf16 v[94:97], v[154:157], v[194:197], v[94:97]
	v_mfma_f32_16x16x32_bf16 v[86:89], v[146:149], v[202:205], v[86:89]
	v_mfma_f32_16x16x32_bf16 v[78:81], v[154:157], v[202:205], v[78:81]
	v_mfma_f32_16x16x32_bf16 v[126:129], v[150:153], v[182:185], v[126:129]
	v_mfma_f32_16x16x32_bf16 v[122:125], v[158:161], v[182:185], v[122:125]
	v_mfma_f32_16x16x32_bf16 v[118:121], v[150:153], v[190:193], v[118:121]
	v_mfma_f32_16x16x32_bf16 v[110:113], v[158:161], v[190:193], v[110:113]
	v_mfma_f32_16x16x32_bf16 v[102:105], v[150:153], v[198:201], v[102:105]
	v_mfma_f32_16x16x32_bf16 v[94:97], v[158:161], v[198:201], v[94:97]
	v_mfma_f32_16x16x32_bf16 v[86:89], v[150:153], v[224:227], v[86:89]
	v_mfma_f32_16x16x32_bf16 v[78:81], v[158:161], v[224:227], v[78:81]
	s_setprio 0
	s_setprio 1
	v_mfma_f32_16x16x32_bf16 v[114:117], v[162:165], v[178:181], v[114:117]
	v_mfma_f32_16x16x32_bf16 v[106:109], v[170:173], v[178:181], v[106:109]
	v_mfma_f32_16x16x32_bf16 v[98:101], v[162:165], v[186:189], v[98:101]
	v_mfma_f32_16x16x32_bf16 v[90:93], v[170:173], v[186:189], v[90:93]
	v_mfma_f32_16x16x32_bf16 v[82:85], v[162:165], v[194:197], v[82:85]
	v_mfma_f32_16x16x32_bf16 v[74:77], v[170:173], v[194:197], v[74:77]
	v_mfma_f32_16x16x32_bf16 v[70:73], v[162:165], v[202:205], v[70:73]
	v_mfma_f32_16x16x32_bf16 v[66:69], v[170:173], v[202:205], v[66:69]
	v_mfma_f32_16x16x32_bf16 v[114:117], v[166:169], v[182:185], v[114:117]
	v_mfma_f32_16x16x32_bf16 v[106:109], v[174:177], v[182:185], v[106:109]
	v_mfma_f32_16x16x32_bf16 v[98:101], v[166:169], v[190:193], v[98:101]
	v_mfma_f32_16x16x32_bf16 v[90:93], v[174:177], v[190:193], v[90:93]
	v_mfma_f32_16x16x32_bf16 v[82:85], v[166:169], v[198:201], v[82:85]
	v_mfma_f32_16x16x32_bf16 v[74:77], v[174:177], v[198:201], v[74:77]
	v_mfma_f32_16x16x32_bf16 v[70:73], v[166:169], v[224:227], v[70:73]
	v_mfma_f32_16x16x32_bf16 v[66:69], v[174:177], v[224:227], v[66:69]
	s_setprio 0
	s_barrier
	s_add_i32 s88, s88, s37
	v_lshl_add_u64 v[140:141], s[28:29], 0, v[16:17]
	s_mov_b32 m0, s88
	ds_read_b128 v[178:181], v145 offset:16384
	ds_read_b128 v[182:185], v145 offset:17408
	ds_read_b128 v[186:189], v145 offset:18432
	ds_read_b128 v[190:193], v145 offset:19456
	ds_read_b128 v[194:197], v145 offset:20480
	ds_read_b128 v[198:201], v145 offset:21504
	ds_read_b128 v[202:205], v145 offset:22528
	ds_read_b128 v[224:227], v145 offset:23552
	global_load_lds_dwordx4 v[140:141], off
	s_add_i32 m0, s88, 0x2000
	s_add_u32 s88, s28, 0x20000
	v_lshl_add_u64 v[206:207], s[28:29], 0, v[130:131]
	s_addc_u32 s89, s29, 0
	s_add_i32 s90, s90, s37
	global_load_lds_dwordx4 v[206:207], off
	v_lshl_add_u64 v[228:229], s[88:89], 0, v[16:17]
	s_mov_b32 m0, s90
	v_lshl_add_u64 v[230:231], s[46:47], 0, v[132:133]
	global_load_lds_dwordx4 v[228:229], off
	v_lshl_add_u64 v[228:229], s[88:89], 0, v[130:131]
	s_add_i32 m0, s90, 0x2000
	s_nop 0
	global_load_lds_dwordx4 v[228:229], off
	v_lshl_add_u64 v[228:229], s[46:47], 0, v[134:135]
	s_mov_b32 m0, s45
	s_nop 0
	global_load_lds_dwordx4 v[228:229], off
	s_mov_b32 m0, s53
	s_nop 0
	global_load_lds_dwordx4 v[230:231], off
	s_waitcnt vmcnt(24)
	s_waitcnt lgkmcnt(0)
	s_barrier
	s_setprio 1
	s_waitcnt lgkmcnt(0)
	v_mfma_f32_16x16x32_bf16 v[62:65], v[146:149], v[178:181], v[62:65]
	v_mfma_f32_16x16x32_bf16 v[58:61], v[154:157], v[178:181], v[58:61]
	v_mfma_f32_16x16x32_bf16 v[54:57], v[146:149], v[186:189], v[54:57]
	v_mfma_f32_16x16x32_bf16 v[46:49], v[154:157], v[186:189], v[46:49]
	v_mfma_f32_16x16x32_bf16 v[38:41], v[146:149], v[194:197], v[38:41]
	v_mfma_f32_16x16x32_bf16 v[30:33], v[154:157], v[194:197], v[30:33]
	v_mfma_f32_16x16x32_bf16 v[22:25], v[146:149], v[202:205], v[22:25]
	v_mfma_f32_16x16x32_bf16 v[12:15], v[154:157], v[202:205], v[12:15]
	v_mfma_f32_16x16x32_bf16 v[62:65], v[150:153], v[182:185], v[62:65]
	v_mfma_f32_16x16x32_bf16 v[58:61], v[158:161], v[182:185], v[58:61]
	v_mfma_f32_16x16x32_bf16 v[54:57], v[150:153], v[190:193], v[54:57]
	v_mfma_f32_16x16x32_bf16 v[46:49], v[158:161], v[190:193], v[46:49]
	v_mfma_f32_16x16x32_bf16 v[38:41], v[150:153], v[198:201], v[38:41]
	v_mfma_f32_16x16x32_bf16 v[30:33], v[158:161], v[198:201], v[30:33]
	v_mfma_f32_16x16x32_bf16 v[22:25], v[150:153], v[224:227], v[22:25]
	v_mfma_f32_16x16x32_bf16 v[12:15], v[158:161], v[224:227], v[12:15]
	s_setprio 0
	s_setprio 1
	v_mfma_f32_16x16x32_bf16 v[50:53], v[162:165], v[178:181], v[50:53]
	v_mfma_f32_16x16x32_bf16 v[42:45], v[170:173], v[178:181], v[42:45]
	v_mfma_f32_16x16x32_bf16 v[34:37], v[162:165], v[186:189], v[34:37]
	v_mfma_f32_16x16x32_bf16 v[26:29], v[170:173], v[186:189], v[26:29]
	v_mfma_f32_16x16x32_bf16 v[18:21], v[162:165], v[194:197], v[18:21]
	v_mfma_f32_16x16x32_bf16 v[8:11], v[170:173], v[194:197], v[8:11]
	v_mfma_f32_16x16x32_bf16 v[4:7], v[162:165], v[202:205], v[4:7]
	v_mfma_f32_16x16x32_bf16 v[0:3], v[170:173], v[202:205], v[0:3]
	v_mfma_f32_16x16x32_bf16 v[50:53], v[166:169], v[182:185], v[50:53]
	v_mfma_f32_16x16x32_bf16 v[42:45], v[174:177], v[182:185], v[42:45]
	v_mfma_f32_16x16x32_bf16 v[34:37], v[166:169], v[190:193], v[34:37]
	v_mfma_f32_16x16x32_bf16 v[26:29], v[174:177], v[190:193], v[26:29]
	v_mfma_f32_16x16x32_bf16 v[18:21], v[166:169], v[198:201], v[18:21]
	v_mfma_f32_16x16x32_bf16 v[8:11], v[174:177], v[198:201], v[8:11]
	v_mfma_f32_16x16x32_bf16 v[4:7], v[166:169], v[224:227], v[4:7]
	v_mfma_f32_16x16x32_bf16 v[0:3], v[174:177], v[224:227], v[0:3]
	s_setprio 0
	s_barrier
	s_add_i32 s88, 0, 0x18000
	s_add_i32 s89, 0, 0x1c000
	v_add_u32_e32 v158, s88, v143
	v_add_u32_e32 v174, s89, v143
	ds_read_b128 v[146:149], v158
	ds_read_b128 v[150:153], v158 offset:1024
	ds_read_b128 v[154:157], v158 offset:2048
	ds_read_b128 v[158:161], v158 offset:3072
	ds_read_b128 v[162:165], v174
	ds_read_b128 v[166:169], v174 offset:1024
	ds_read_b128 v[170:173], v174 offset:2048
	ds_read_b128 v[174:177], v174 offset:3072
	s_add_u32 s46, s46, 0x80000
	s_addc_u32 s47, s47, 0
	s_mov_b32 m0, s58
	v_lshl_add_u64 v[232:233], s[46:47], 0, v[134:135]
	ds_read_b128 v[178:181], v145 offset:32768
	ds_read_b128 v[182:185], v145 offset:33792
	ds_read_b128 v[186:189], v145 offset:34816
	ds_read_b128 v[190:193], v145 offset:35840
	ds_read_b128 v[194:197], v145 offset:36864
	ds_read_b128 v[198:201], v145 offset:37888
	ds_read_b128 v[202:205], v145 offset:38912
	ds_read_b128 v[224:227], v145 offset:39936
	global_load_lds_dwordx4 v[232:233], off
	v_lshl_add_u64 v[232:233], s[46:47], 0, v[132:133]
	s_mov_b32 m0, s59
	s_nop 0
	global_load_lds_dwordx4 v[232:233], off
	s_waitcnt vmcnt(8)
	s_waitcnt lgkmcnt(0)
	s_barrier
	s_setprio 1
	s_waitcnt lgkmcnt(0)
	v_mfma_f32_16x16x32_bf16 v[126:129], v[146:149], v[178:181], v[126:129]
	v_mfma_f32_16x16x32_bf16 v[122:125], v[154:157], v[178:181], v[122:125]
	v_mfma_f32_16x16x32_bf16 v[118:121], v[146:149], v[186:189], v[118:121]
	v_mfma_f32_16x16x32_bf16 v[110:113], v[154:157], v[186:189], v[110:113]
	v_mfma_f32_16x16x32_bf16 v[102:105], v[146:149], v[194:197], v[102:105]
	v_mfma_f32_16x16x32_bf16 v[94:97], v[154:157], v[194:197], v[94:97]
	v_mfma_f32_16x16x32_bf16 v[86:89], v[146:149], v[202:205], v[86:89]
	v_mfma_f32_16x16x32_bf16 v[78:81], v[154:157], v[202:205], v[78:81]
	v_mfma_f32_16x16x32_bf16 v[126:129], v[150:153], v[182:185], v[126:129]
	v_mfma_f32_16x16x32_bf16 v[122:125], v[158:161], v[182:185], v[122:125]
	v_mfma_f32_16x16x32_bf16 v[118:121], v[150:153], v[190:193], v[118:121]
	v_mfma_f32_16x16x32_bf16 v[110:113], v[158:161], v[190:193], v[110:113]
	v_mfma_f32_16x16x32_bf16 v[102:105], v[150:153], v[198:201], v[102:105]
	v_mfma_f32_16x16x32_bf16 v[94:97], v[158:161], v[198:201], v[94:97]
	v_mfma_f32_16x16x32_bf16 v[86:89], v[150:153], v[224:227], v[86:89]
	v_mfma_f32_16x16x32_bf16 v[78:81], v[158:161], v[224:227], v[78:81]
	s_setprio 0
	s_setprio 1
	v_mfma_f32_16x16x32_bf16 v[114:117], v[162:165], v[178:181], v[114:117]
	v_mfma_f32_16x16x32_bf16 v[106:109], v[170:173], v[178:181], v[106:109]
	v_mfma_f32_16x16x32_bf16 v[98:101], v[162:165], v[186:189], v[98:101]
	v_mfma_f32_16x16x32_bf16 v[90:93], v[170:173], v[186:189], v[90:93]
	v_mfma_f32_16x16x32_bf16 v[82:85], v[162:165], v[194:197], v[82:85]
	v_mfma_f32_16x16x32_bf16 v[74:77], v[170:173], v[194:197], v[74:77]
	v_mfma_f32_16x16x32_bf16 v[70:73], v[162:165], v[202:205], v[70:73]
	v_mfma_f32_16x16x32_bf16 v[66:69], v[170:173], v[202:205], v[66:69]
	v_mfma_f32_16x16x32_bf16 v[114:117], v[166:169], v[182:185], v[114:117]
	v_mfma_f32_16x16x32_bf16 v[106:109], v[174:177], v[182:185], v[106:109]
	v_mfma_f32_16x16x32_bf16 v[98:101], v[166:169], v[190:193], v[98:101]
	v_mfma_f32_16x16x32_bf16 v[90:93], v[174:177], v[190:193], v[90:93]
	v_mfma_f32_16x16x32_bf16 v[82:85], v[166:169], v[198:201], v[82:85]
	v_mfma_f32_16x16x32_bf16 v[74:77], v[174:177], v[198:201], v[74:77]
	v_mfma_f32_16x16x32_bf16 v[70:73], v[166:169], v[224:227], v[70:73]
	v_mfma_f32_16x16x32_bf16 v[66:69], v[174:177], v[224:227], v[66:69]
	s_setprio 0
	s_barrier
	s_add_i32 s46, s88, s37
	v_lshl_add_u64 v[140:141], v[140:141], 0, s[34:35]
	s_mov_b32 m0, s46
	ds_read_b128 v[178:181], v145 offset:49152
	ds_read_b128 v[182:185], v145 offset:50176
	ds_read_b128 v[186:189], v145 offset:51200
	ds_read_b128 v[190:193], v145 offset:52224
	ds_read_b128 v[194:197], v145 offset:53248
	ds_read_b128 v[198:201], v145 offset:54272
	ds_read_b128 v[202:205], v145 offset:55296
	ds_read_b128 v[224:227], v145 offset:56320
	global_load_lds_dwordx4 v[140:141], off
	s_add_i32 m0, s46, 0x2000
	s_add_u32 s28, s28, 0x20080
	v_lshl_add_u64 v[140:141], v[206:207], 0, s[34:35]
	s_addc_u32 s29, s29, 0
	s_add_i32 s46, s89, s37
	global_load_lds_dwordx4 v[140:141], off
	v_lshl_add_u64 v[140:141], s[28:29], 0, v[16:17]
	s_mov_b32 m0, s46
	s_nop 0
	global_load_lds_dwordx4 v[140:141], off
	v_lshl_add_u64 v[140:141], s[28:29], 0, v[130:131]
	s_add_i32 m0, s46, 0x2000
	s_nop 0
	global_load_lds_dwordx4 v[140:141], off
	v_lshl_add_u64 v[140:141], v[228:229], 0, s[34:35]
	s_mov_b32 m0, s83
	s_nop 0
	global_load_lds_dwordx4 v[140:141], off
	v_lshl_add_u64 v[140:141], v[230:231], 0, s[34:35]
	s_mov_b32 m0, s84
	s_nop 0
	global_load_lds_dwordx4 v[140:141], off
	s_waitcnt vmcnt(8)
	s_waitcnt lgkmcnt(0)
	s_barrier
	s_setprio 1
	s_waitcnt lgkmcnt(0)
	v_mfma_f32_16x16x32_bf16 v[62:65], v[146:149], v[178:181], v[62:65]
	v_mfma_f32_16x16x32_bf16 v[58:61], v[154:157], v[178:181], v[58:61]
	v_mfma_f32_16x16x32_bf16 v[54:57], v[146:149], v[186:189], v[54:57]
	v_mfma_f32_16x16x32_bf16 v[46:49], v[154:157], v[186:189], v[46:49]
	v_mfma_f32_16x16x32_bf16 v[38:41], v[146:149], v[194:197], v[38:41]
	v_mfma_f32_16x16x32_bf16 v[30:33], v[154:157], v[194:197], v[30:33]
	v_mfma_f32_16x16x32_bf16 v[22:25], v[146:149], v[202:205], v[22:25]
	v_mfma_f32_16x16x32_bf16 v[12:15], v[154:157], v[202:205], v[12:15]
	v_mfma_f32_16x16x32_bf16 v[62:65], v[150:153], v[182:185], v[62:65]
	v_mfma_f32_16x16x32_bf16 v[58:61], v[158:161], v[182:185], v[58:61]
	v_mfma_f32_16x16x32_bf16 v[54:57], v[150:153], v[190:193], v[54:57]
	v_mfma_f32_16x16x32_bf16 v[46:49], v[158:161], v[190:193], v[46:49]
	v_mfma_f32_16x16x32_bf16 v[38:41], v[150:153], v[198:201], v[38:41]
	v_mfma_f32_16x16x32_bf16 v[30:33], v[158:161], v[198:201], v[30:33]
	v_mfma_f32_16x16x32_bf16 v[22:25], v[150:153], v[224:227], v[22:25]
	v_mfma_f32_16x16x32_bf16 v[12:15], v[158:161], v[224:227], v[12:15]
	s_setprio 0
	s_setprio 1
	v_mfma_f32_16x16x32_bf16 v[50:53], v[162:165], v[178:181], v[50:53]
	v_mfma_f32_16x16x32_bf16 v[42:45], v[170:173], v[178:181], v[42:45]
	v_mfma_f32_16x16x32_bf16 v[34:37], v[162:165], v[186:189], v[34:37]
	v_mfma_f32_16x16x32_bf16 v[26:29], v[170:173], v[186:189], v[26:29]
	v_mfma_f32_16x16x32_bf16 v[18:21], v[162:165], v[194:197], v[18:21]
	v_mfma_f32_16x16x32_bf16 v[8:11], v[170:173], v[194:197], v[8:11]
	v_mfma_f32_16x16x32_bf16 v[4:7], v[162:165], v[202:205], v[4:7]
	v_mfma_f32_16x16x32_bf16 v[0:3], v[170:173], v[202:205], v[0:3]
	v_mfma_f32_16x16x32_bf16 v[50:53], v[166:169], v[182:185], v[50:53]
	v_mfma_f32_16x16x32_bf16 v[42:45], v[174:177], v[182:185], v[42:45]
	v_mfma_f32_16x16x32_bf16 v[34:37], v[166:169], v[190:193], v[34:37]
	v_mfma_f32_16x16x32_bf16 v[26:29], v[174:177], v[190:193], v[26:29]
	v_mfma_f32_16x16x32_bf16 v[18:21], v[166:169], v[198:201], v[18:21]
	v_mfma_f32_16x16x32_bf16 v[8:11], v[174:177], v[198:201], v[8:11]
	v_mfma_f32_16x16x32_bf16 v[4:7], v[166:169], v[224:227], v[4:7]
	v_mfma_f32_16x16x32_bf16 v[0:3], v[174:177], v[224:227], v[0:3]
	s_setprio 0
	s_barrier
	s_add_i32 s87, s87, 2
	s_add_u32 s40, s40, 0x100
	s_addc_u32 s41, s41, 0
	s_add_u32 s48, s48, 0x100
	s_addc_u32 s49, s49, 0
	s_cmp_gt_u32 s87, 5
	s_cbranch_scc1 .Lpk_E_exit

.LBB0_716:
	s_ashr_i32 s23, s22, 31
	s_lshl_b64 s[26:27], s[22:23], 20
	s_add_u32 s26, s68, s26
	s_addc_u32 s27, s69, s27
	s_and_b64 s[28:29], s[38:39], exec
	s_cselect_b32 s23, s27, s45
	s_cselect_b32 s84, s26, s44
	s_ashr_i32 s19, s18, 31
	s_lshl_b64 s[28:29], s[18:19], 20
	v_readlane_b32 s19, v255, 12
	s_add_u32 s40, s19, s28
	v_readlane_b32 s19, v255, 13
	s_addc_u32 s41, s19, s29
	s_and_b64 s[28:29], s[38:39], exec
	s_cselect_b32 s19, s41, s47
	s_cselect_b32 s85, s40, s46
	s_add_u32 s44, s44, 0x80080
	s_addc_u32 s45, s45, 0
	s_add_u32 s86, s46, 0x100
	v_mov_b32_e32 v0, 0
	s_addc_u32 s87, s47, 0
	s_mov_b32 s88, -2
	v_mov_b32_e32 v1, v0
	v_mov_b32_e32 v2, v0
	v_mov_b32_e32 v3, v0
	v_mov_b32_e32 v4, v0
	v_mov_b32_e32 v5, v0
	v_mov_b32_e32 v6, v0
	v_mov_b32_e32 v7, v0
	v_mov_b32_e32 v8, v0
	v_mov_b32_e32 v9, v0
	v_mov_b32_e32 v10, v0
	v_mov_b32_e32 v11, v0
	v_mov_b32_e32 v12, v0
	v_mov_b32_e32 v13, v0
	v_mov_b32_e32 v14, v0
	v_mov_b32_e32 v15, v0
	v_mov_b32_e32 v18, v0
	v_mov_b32_e32 v19, v0
	v_mov_b32_e32 v20, v0
	v_mov_b32_e32 v21, v0
	v_mov_b32_e32 v22, v0
	v_mov_b32_e32 v23, v0
	v_mov_b32_e32 v24, v0
	v_mov_b32_e32 v25, v0
	v_mov_b32_e32 v26, v0
	v_mov_b32_e32 v27, v0
	v_mov_b32_e32 v28, v0
	v_mov_b32_e32 v29, v0
	v_mov_b32_e32 v30, v0
	v_mov_b32_e32 v31, v0
	v_mov_b32_e32 v32, v0
	v_mov_b32_e32 v33, v0
	v_mov_b32_e32 v34, v0
	v_mov_b32_e32 v35, v0
	v_mov_b32_e32 v36, v0
	v_mov_b32_e32 v37, v0
	v_mov_b32_e32 v38, v0
	v_mov_b32_e32 v39, v0
	v_mov_b32_e32 v40, v0
	v_mov_b32_e32 v41, v0
	v_mov_b32_e32 v42, v0
	v_mov_b32_e32 v43, v0
	v_mov_b32_e32 v44, v0
	v_mov_b32_e32 v45, v0
	v_mov_b32_e32 v46, v0
	v_mov_b32_e32 v47, v0
	v_mov_b32_e32 v48, v0
	v_mov_b32_e32 v49, v0
	v_mov_b32_e32 v50, v0
	v_mov_b32_e32 v51, v0
	v_mov_b32_e32 v52, v0
	v_mov_b32_e32 v53, v0
	v_mov_b32_e32 v54, v0
	v_mov_b32_e32 v55, v0
	v_mov_b32_e32 v56, v0
	v_mov_b32_e32 v57, v0
	v_mov_b32_e32 v58, v0
	v_mov_b32_e32 v59, v0
	v_mov_b32_e32 v60, v0
	v_mov_b32_e32 v61, v0
	v_mov_b32_e32 v62, v0
	v_mov_b32_e32 v63, v0
	v_mov_b32_e32 v64, v0
	v_mov_b32_e32 v65, v0
	v_mov_b32_e32 v66, v0
	v_mov_b32_e32 v67, v0
	v_mov_b32_e32 v68, v0
	v_mov_b32_e32 v69, v0
	v_mov_b32_e32 v70, v0
	v_mov_b32_e32 v71, v0
	v_mov_b32_e32 v72, v0
	v_mov_b32_e32 v73, v0
	v_mov_b32_e32 v74, v0
	v_mov_b32_e32 v75, v0
	v_mov_b32_e32 v76, v0
	v_mov_b32_e32 v77, v0
	v_mov_b32_e32 v78, v0
	v_mov_b32_e32 v79, v0
	v_mov_b32_e32 v80, v0
	v_mov_b32_e32 v81, v0
	v_mov_b32_e32 v82, v0
	v_mov_b32_e32 v83, v0
	v_mov_b32_e32 v84, v0
	v_mov_b32_e32 v85, v0
	v_mov_b32_e32 v86, v0
	v_mov_b32_e32 v87, v0
	v_mov_b32_e32 v88, v0
	v_mov_b32_e32 v89, v0
	v_mov_b32_e32 v90, v0
	v_mov_b32_e32 v91, v0
	v_mov_b32_e32 v92, v0
	v_mov_b32_e32 v93, v0
	v_mov_b32_e32 v94, v0
	v_mov_b32_e32 v95, v0
	v_mov_b32_e32 v96, v0
	v_mov_b32_e32 v97, v0
	v_mov_b32_e32 v98, v0
	v_mov_b32_e32 v99, v0
	v_mov_b32_e32 v100, v0
	v_mov_b32_e32 v101, v0
	v_mov_b32_e32 v102, v0
	v_mov_b32_e32 v103, v0
	v_mov_b32_e32 v104, v0
	v_mov_b32_e32 v105, v0
	v_mov_b32_e32 v106, v0
	v_mov_b32_e32 v107, v0
	v_mov_b32_e32 v108, v0
	v_mov_b32_e32 v109, v0
	v_mov_b32_e32 v110, v0
	v_mov_b32_e32 v111, v0
	v_mov_b32_e32 v112, v0
	v_mov_b32_e32 v113, v0
	v_mov_b32_e32 v114, v0
	v_mov_b32_e32 v115, v0
	v_mov_b32_e32 v116, v0
	v_mov_b32_e32 v117, v0
	v_mov_b32_e32 v118, v0
	v_mov_b32_e32 v119, v0
	v_mov_b32_e32 v120, v0
	v_mov_b32_e32 v121, v0
	v_mov_b32_e32 v122, v0
	v_mov_b32_e32 v123, v0
	v_mov_b32_e32 v124, v0
	v_mov_b32_e32 v125, v0
	v_mov_b32_e32 v126, v0
	v_mov_b32_e32 v127, v0
	v_mov_b32_e32 v128, v0
	v_mov_b32_e32 v129, v0
	s_cmp_eq_u32 s59, 1
	s_cbranch_scc1 .LBB0_717
	s_add_u32 s28, s44, 0xfff80080
	s_addc_u32 s29, s45, -1
	s_add_i32 s89, 0, 0x10000
	s_cmp_eq_u32 s88, 28
	s_cselect_b32 s47, s23, s29
	s_cselect_b32 s46, s84, s28
	s_cselect_b32 s29, s19, s87
	s_cselect_b32 s28, s85, s86
	s_add_i32 s92, 0, 0x14000
	v_add_u32_e32 v148, s89, v224
	v_add_u32_e32 v164, s92, v224
	ds_read_b128 v[136:139], v148
	ds_read_b128 v[140:143], v148 offset:1024
	ds_read_b128 v[144:147], v148 offset:2048
	ds_read_b128 v[148:151], v148 offset:3072
	ds_read_b128 v[152:155], v164
	ds_read_b128 v[156:159], v164 offset:1024
	ds_read_b128 v[160:163], v164 offset:2048
	ds_read_b128 v[164:167], v164 offset:3072
	v_lshl_add_u64 v[200:201], s[44:45], 0, v[132:133]
	s_add_i32 m0, s43, 0xc000
	ds_read_b128 v[168:171], v226
	ds_read_b128 v[172:175], v226 offset:1024
	ds_read_b128 v[176:179], v226 offset:2048
	ds_read_b128 v[180:183], v226 offset:3072
	ds_read_b128 v[184:187], v226 offset:4096
	ds_read_b128 v[188:191], v226 offset:5120
	ds_read_b128 v[192:195], v226 offset:6144
	ds_read_b128 v[196:199], v226 offset:7168
	global_load_lds_dwordx4 v[200:201], off
	v_lshl_add_u64 v[200:201], s[44:45], 0, v[134:135]
	s_add_i32 m0, s43, 0xe000
	s_nop 0
	global_load_lds_dwordx4 v[200:201], off
	s_waitcnt vmcnt(16)
	s_waitcnt lgkmcnt(0)
	s_barrier
	s_setprio 1
	s_waitcnt lgkmcnt(0)
	v_mfma_f32_16x16x32_bf16 v[126:129], v[136:139], v[168:171], v[126:129]
	v_mfma_f32_16x16x32_bf16 v[122:125], v[144:147], v[168:171], v[122:125]
	v_mfma_f32_16x16x32_bf16 v[118:121], v[136:139], v[176:179], v[118:121]
	v_mfma_f32_16x16x32_bf16 v[114:117], v[144:147], v[176:179], v[114:117]
	v_mfma_f32_16x16x32_bf16 v[110:113], v[136:139], v[184:187], v[110:113]
	v_mfma_f32_16x16x32_bf16 v[106:109], v[144:147], v[184:187], v[106:109]
	v_mfma_f32_16x16x32_bf16 v[102:105], v[136:139], v[192:195], v[102:105]
	v_mfma_f32_16x16x32_bf16 v[98:101], v[144:147], v[192:195], v[98:101]
	v_mfma_f32_16x16x32_bf16 v[126:129], v[140:143], v[172:175], v[126:129]
	v_mfma_f32_16x16x32_bf16 v[122:125], v[148:151], v[172:175], v[122:125]
	v_mfma_f32_16x16x32_bf16 v[118:121], v[140:143], v[180:183], v[118:121]
	v_mfma_f32_16x16x32_bf16 v[114:117], v[148:151], v[180:183], v[114:117]
	v_mfma_f32_16x16x32_bf16 v[110:113], v[140:143], v[188:191], v[110:113]
	v_mfma_f32_16x16x32_bf16 v[106:109], v[148:151], v[188:191], v[106:109]
	v_mfma_f32_16x16x32_bf16 v[102:105], v[140:143], v[196:199], v[102:105]
	v_mfma_f32_16x16x32_bf16 v[98:101], v[148:151], v[196:199], v[98:101]
	s_setprio 0
	s_setprio 1
	v_mfma_f32_16x16x32_bf16 v[94:97], v[152:155], v[168:171], v[94:97]
	v_mfma_f32_16x16x32_bf16 v[90:93], v[160:163], v[168:171], v[90:93]
	v_mfma_f32_16x16x32_bf16 v[86:89], v[152:155], v[176:179], v[86:89]
	v_mfma_f32_16x16x32_bf16 v[82:85], v[160:163], v[176:179], v[82:85]
	v_mfma_f32_16x16x32_bf16 v[78:81], v[152:155], v[184:187], v[78:81]
	v_mfma_f32_16x16x32_bf16 v[74:77], v[160:163], v[184:187], v[74:77]
	v_mfma_f32_16x16x32_bf16 v[70:73], v[152:155], v[192:195], v[70:73]
	v_mfma_f32_16x16x32_bf16 v[66:69], v[160:163], v[192:195], v[66:69]
	v_mfma_f32_16x16x32_bf16 v[94:97], v[156:159], v[172:175], v[94:97]
	v_mfma_f32_16x16x32_bf16 v[90:93], v[164:167], v[172:175], v[90:93]
	v_mfma_f32_16x16x32_bf16 v[86:89], v[156:159], v[180:183], v[86:89]
	v_mfma_f32_16x16x32_bf16 v[82:85], v[164:167], v[180:183], v[82:85]
	v_mfma_f32_16x16x32_bf16 v[78:81], v[156:159], v[188:191], v[78:81]
	v_mfma_f32_16x16x32_bf16 v[74:77], v[164:167], v[188:191], v[74:77]
	v_mfma_f32_16x16x32_bf16 v[70:73], v[156:159], v[196:199], v[70:73]
	v_mfma_f32_16x16x32_bf16 v[66:69], v[164:167], v[196:199], v[66:69]
	s_setprio 0
	s_barrier
	s_add_i32 s89, s89, s37
	v_lshl_add_u64 v[200:201], s[28:29], 0, v[16:17]
	s_mov_b32 m0, s89
	ds_read_b128 v[168:171], v226 offset:16384
	ds_read_b128 v[172:175], v226 offset:17408
	ds_read_b128 v[176:179], v226 offset:18432
	ds_read_b128 v[180:183], v226 offset:19456
	ds_read_b128 v[184:187], v226 offset:20480
	ds_read_b128 v[188:191], v226 offset:21504
	ds_read_b128 v[192:195], v226 offset:22528
	ds_read_b128 v[196:199], v226 offset:23552
	global_load_lds_dwordx4 v[200:201], off
	s_add_i32 m0, s89, 0x2000
	s_add_u32 s90, s28, 0x80000
	v_lshl_add_u64 v[202:203], s[28:29], 0, v[130:131]
	s_addc_u32 s91, s29, 0
	s_add_i32 s89, s92, s37
	global_load_lds_dwordx4 v[202:203], off
	v_lshl_add_u64 v[204:205], s[90:91], 0, v[16:17]
	s_mov_b32 m0, s89
	v_lshl_add_u64 v[206:207], s[46:47], 0, v[130:131]
	global_load_lds_dwordx4 v[204:205], off
	v_lshl_add_u64 v[204:205], s[90:91], 0, v[130:131]
	s_add_i32 m0, s89, 0x2000
	s_nop 0
	global_load_lds_dwordx4 v[204:205], off
	v_lshl_add_u64 v[204:205], s[46:47], 0, v[16:17]
	s_mov_b32 m0, s43
	s_nop 0
	global_load_lds_dwordx4 v[204:205], off
	s_mov_b32 m0, s50
	s_nop 0
	global_load_lds_dwordx4 v[206:207], off
	s_waitcnt vmcnt(16)
	s_waitcnt lgkmcnt(0)
	s_barrier
	s_setprio 1
	s_waitcnt lgkmcnt(0)
	v_mfma_f32_16x16x32_bf16 v[62:65], v[136:139], v[168:171], v[62:65]
	v_mfma_f32_16x16x32_bf16 v[58:61], v[144:147], v[168:171], v[58:61]
	v_mfma_f32_16x16x32_bf16 v[54:57], v[136:139], v[176:179], v[54:57]
	v_mfma_f32_16x16x32_bf16 v[50:53], v[144:147], v[176:179], v[50:53]
	v_mfma_f32_16x16x32_bf16 v[46:49], v[136:139], v[184:187], v[46:49]
	v_mfma_f32_16x16x32_bf16 v[42:45], v[144:147], v[184:187], v[42:45]
	v_mfma_f32_16x16x32_bf16 v[38:41], v[136:139], v[192:195], v[38:41]
	v_mfma_f32_16x16x32_bf16 v[34:37], v[144:147], v[192:195], v[34:37]
	v_mfma_f32_16x16x32_bf16 v[62:65], v[140:143], v[172:175], v[62:65]
	v_mfma_f32_16x16x32_bf16 v[58:61], v[148:151], v[172:175], v[58:61]
	v_mfma_f32_16x16x32_bf16 v[54:57], v[140:143], v[180:183], v[54:57]
	v_mfma_f32_16x16x32_bf16 v[50:53], v[148:151], v[180:183], v[50:53]
	v_mfma_f32_16x16x32_bf16 v[46:49], v[140:143], v[188:191], v[46:49]
	v_mfma_f32_16x16x32_bf16 v[42:45], v[148:151], v[188:191], v[42:45]
	v_mfma_f32_16x16x32_bf16 v[38:41], v[140:143], v[196:199], v[38:41]
	v_mfma_f32_16x16x32_bf16 v[34:37], v[148:151], v[196:199], v[34:37]
	s_setprio 0
	s_setprio 1
	v_mfma_f32_16x16x32_bf16 v[30:33], v[152:155], v[168:171], v[30:33]
	v_mfma_f32_16x16x32_bf16 v[26:29], v[160:163], v[168:171], v[26:29]
	v_mfma_f32_16x16x32_bf16 v[22:25], v[152:155], v[176:179], v[22:25]
	v_mfma_f32_16x16x32_bf16 v[18:21], v[160:163], v[176:179], v[18:21]
	v_mfma_f32_16x16x32_bf16 v[12:15], v[152:155], v[184:187], v[12:15]
	v_mfma_f32_16x16x32_bf16 v[8:11], v[160:163], v[184:187], v[8:11]
	v_mfma_f32_16x16x32_bf16 v[4:7], v[152:155], v[192:195], v[4:7]
	v_mfma_f32_16x16x32_bf16 v[0:3], v[160:163], v[192:195], v[0:3]
	v_mfma_f32_16x16x32_bf16 v[30:33], v[156:159], v[172:175], v[30:33]
	v_mfma_f32_16x16x32_bf16 v[26:29], v[164:167], v[172:175], v[26:29]
	v_mfma_f32_16x16x32_bf16 v[22:25], v[156:159], v[180:183], v[22:25]
	v_mfma_f32_16x16x32_bf16 v[18:21], v[164:167], v[180:183], v[18:21]
	v_mfma_f32_16x16x32_bf16 v[12:15], v[156:159], v[188:191], v[12:15]
	v_mfma_f32_16x16x32_bf16 v[8:11], v[164:167], v[188:191], v[8:11]
	v_mfma_f32_16x16x32_bf16 v[4:7], v[156:159], v[196:199], v[4:7]
	v_mfma_f32_16x16x32_bf16 v[0:3], v[164:167], v[196:199], v[0:3]
	s_setprio 0
	s_barrier
	s_add_i32 s89, 0, 0x18000
	s_add_i32 s90, 0, 0x1c000
	v_add_u32_e32 v148, s89, v224
	v_add_u32_e32 v164, s90, v224
	ds_read_b128 v[136:139], v148
	ds_read_b128 v[140:143], v148 offset:1024
	ds_read_b128 v[144:147], v148 offset:2048
	ds_read_b128 v[148:151], v148 offset:3072
	ds_read_b128 v[152:155], v164
	ds_read_b128 v[156:159], v164 offset:1024
	ds_read_b128 v[160:163], v164 offset:2048
	ds_read_b128 v[164:167], v164 offset:3072
	s_add_u32 s46, s46, 0x80000
	s_addc_u32 s47, s47, 0
	s_mov_b32 m0, s51
	v_lshl_add_u64 v[228:229], s[46:47], 0, v[16:17]
	ds_read_b128 v[168:171], v226 offset:32768
	ds_read_b128 v[172:175], v226 offset:33792
	ds_read_b128 v[176:179], v226 offset:34816
	ds_read_b128 v[180:183], v226 offset:35840
	ds_read_b128 v[184:187], v226 offset:36864
	ds_read_b128 v[188:191], v226 offset:37888
	ds_read_b128 v[192:195], v226 offset:38912
	ds_read_b128 v[196:199], v226 offset:39936
	global_load_lds_dwordx4 v[228:229], off
	v_lshl_add_u64 v[228:229], s[46:47], 0, v[130:131]
	s_mov_b32 m0, s52
	s_nop 0
	global_load_lds_dwordx4 v[228:229], off
	s_waitcnt vmcnt(8)
	s_waitcnt lgkmcnt(0)
	s_barrier
	s_setprio 1
	s_waitcnt lgkmcnt(0)
	v_mfma_f32_16x16x32_bf16 v[126:129], v[136:139], v[168:171], v[126:129]
	v_mfma_f32_16x16x32_bf16 v[122:125], v[144:147], v[168:171], v[122:125]
	v_mfma_f32_16x16x32_bf16 v[118:121], v[136:139], v[176:179], v[118:121]
	v_mfma_f32_16x16x32_bf16 v[114:117], v[144:147], v[176:179], v[114:117]
	v_mfma_f32_16x16x32_bf16 v[110:113], v[136:139], v[184:187], v[110:113]
	v_mfma_f32_16x16x32_bf16 v[106:109], v[144:147], v[184:187], v[106:109]
	v_mfma_f32_16x16x32_bf16 v[102:105], v[136:139], v[192:195], v[102:105]
	v_mfma_f32_16x16x32_bf16 v[98:101], v[144:147], v[192:195], v[98:101]
	v_mfma_f32_16x16x32_bf16 v[126:129], v[140:143], v[172:175], v[126:129]
	v_mfma_f32_16x16x32_bf16 v[122:125], v[148:151], v[172:175], v[122:125]
	v_mfma_f32_16x16x32_bf16 v[118:121], v[140:143], v[180:183], v[118:121]
	v_mfma_f32_16x16x32_bf16 v[114:117], v[148:151], v[180:183], v[114:117]
	v_mfma_f32_16x16x32_bf16 v[110:113], v[140:143], v[188:191], v[110:113]
	v_mfma_f32_16x16x32_bf16 v[106:109], v[148:151], v[188:191], v[106:109]
	v_mfma_f32_16x16x32_bf16 v[102:105], v[140:143], v[196:199], v[102:105]
	v_mfma_f32_16x16x32_bf16 v[98:101], v[148:151], v[196:199], v[98:101]
	s_setprio 0
	s_setprio 1
	v_mfma_f32_16x16x32_bf16 v[94:97], v[152:155], v[168:171], v[94:97]
	v_mfma_f32_16x16x32_bf16 v[90:93], v[160:163], v[168:171], v[90:93]
	v_mfma_f32_16x16x32_bf16 v[86:89], v[152:155], v[176:179], v[86:89]
	v_mfma_f32_16x16x32_bf16 v[82:85], v[160:163], v[176:179], v[82:85]
	v_mfma_f32_16x16x32_bf16 v[78:81], v[152:155], v[184:187], v[78:81]
	v_mfma_f32_16x16x32_bf16 v[74:77], v[160:163], v[184:187], v[74:77]
	v_mfma_f32_16x16x32_bf16 v[70:73], v[152:155], v[192:195], v[70:73]
	v_mfma_f32_16x16x32_bf16 v[66:69], v[160:163], v[192:195], v[66:69]
	v_mfma_f32_16x16x32_bf16 v[94:97], v[156:159], v[172:175], v[94:97]
	v_mfma_f32_16x16x32_bf16 v[90:93], v[164:167], v[172:175], v[90:93]
	v_mfma_f32_16x16x32_bf16 v[86:89], v[156:159], v[180:183], v[86:89]
	v_mfma_f32_16x16x32_bf16 v[82:85], v[164:167], v[180:183], v[82:85]
	v_mfma_f32_16x16x32_bf16 v[78:81], v[156:159], v[188:191], v[78:81]
	v_mfma_f32_16x16x32_bf16 v[74:77], v[164:167], v[188:191], v[74:77]
	v_mfma_f32_16x16x32_bf16 v[70:73], v[156:159], v[196:199], v[70:73]
	v_mfma_f32_16x16x32_bf16 v[66:69], v[164:167], v[196:199], v[66:69]
	s_setprio 0
	s_barrier
	s_add_i32 s46, s89, s37
	v_lshl_add_u64 v[200:201], v[200:201], 0, s[34:35]
	s_mov_b32 m0, s46
	ds_read_b128 v[168:171], v226 offset:49152
	ds_read_b128 v[172:175], v226 offset:50176
	ds_read_b128 v[176:179], v226 offset:51200
	ds_read_b128 v[180:183], v226 offset:52224
	ds_read_b128 v[184:187], v226 offset:53248
	ds_read_b128 v[188:191], v226 offset:54272
	ds_read_b128 v[192:195], v226 offset:55296
	ds_read_b128 v[196:199], v226 offset:56320
	global_load_lds_dwordx4 v[200:201], off
	s_add_i32 m0, s46, 0x2000
	s_add_u32 s28, s28, 0x80080
	v_lshl_add_u64 v[200:201], v[202:203], 0, s[34:35]
	s_addc_u32 s29, s29, 0
	s_add_i32 s46, s90, s37
	global_load_lds_dwordx4 v[200:201], off
	v_lshl_add_u64 v[200:201], s[28:29], 0, v[16:17]
	s_mov_b32 m0, s46
	s_nop 0
	global_load_lds_dwordx4 v[200:201], off
	v_lshl_add_u64 v[200:201], s[28:29], 0, v[130:131]
	s_add_i32 m0, s46, 0x2000
	s_nop 0
	global_load_lds_dwordx4 v[200:201], off
	v_lshl_add_u64 v[200:201], v[204:205], 0, s[34:35]
	s_mov_b32 m0, s53
	s_nop 0
	global_load_lds_dwordx4 v[200:201], off
	v_lshl_add_u64 v[200:201], v[206:207], 0, s[34:35]
	s_mov_b32 m0, s58
	s_nop 0
	global_load_lds_dwordx4 v[200:201], off
	s_waitcnt vmcnt(8)
	s_waitcnt lgkmcnt(0)
	s_barrier
	s_setprio 1
	s_waitcnt lgkmcnt(0)
	v_mfma_f32_16x16x32_bf16 v[62:65], v[136:139], v[168:171], v[62:65]
	v_mfma_f32_16x16x32_bf16 v[58:61], v[144:147], v[168:171], v[58:61]
	v_mfma_f32_16x16x32_bf16 v[54:57], v[136:139], v[176:179], v[54:57]
	v_mfma_f32_16x16x32_bf16 v[50:53], v[144:147], v[176:179], v[50:53]
	v_mfma_f32_16x16x32_bf16 v[46:49], v[136:139], v[184:187], v[46:49]
	v_mfma_f32_16x16x32_bf16 v[42:45], v[144:147], v[184:187], v[42:45]
	v_mfma_f32_16x16x32_bf16 v[38:41], v[136:139], v[192:195], v[38:41]
	v_mfma_f32_16x16x32_bf16 v[34:37], v[144:147], v[192:195], v[34:37]
	v_mfma_f32_16x16x32_bf16 v[62:65], v[140:143], v[172:175], v[62:65]
	v_mfma_f32_16x16x32_bf16 v[58:61], v[148:151], v[172:175], v[58:61]
	v_mfma_f32_16x16x32_bf16 v[54:57], v[140:143], v[180:183], v[54:57]
	v_mfma_f32_16x16x32_bf16 v[50:53], v[148:151], v[180:183], v[50:53]
	v_mfma_f32_16x16x32_bf16 v[46:49], v[140:143], v[188:191], v[46:49]
	v_mfma_f32_16x16x32_bf16 v[42:45], v[148:151], v[188:191], v[42:45]
	v_mfma_f32_16x16x32_bf16 v[38:41], v[140:143], v[196:199], v[38:41]
	v_mfma_f32_16x16x32_bf16 v[34:37], v[148:151], v[196:199], v[34:37]
	s_setprio 0
	s_setprio 1
	v_mfma_f32_16x16x32_bf16 v[30:33], v[152:155], v[168:171], v[30:33]
	v_mfma_f32_16x16x32_bf16 v[26:29], v[160:163], v[168:171], v[26:29]
	v_mfma_f32_16x16x32_bf16 v[22:25], v[152:155], v[176:179], v[22:25]
	v_mfma_f32_16x16x32_bf16 v[18:21], v[160:163], v[176:179], v[18:21]
	v_mfma_f32_16x16x32_bf16 v[12:15], v[152:155], v[184:187], v[12:15]
	v_mfma_f32_16x16x32_bf16 v[8:11], v[160:163], v[184:187], v[8:11]
	v_mfma_f32_16x16x32_bf16 v[4:7], v[152:155], v[192:195], v[4:7]
	v_mfma_f32_16x16x32_bf16 v[0:3], v[160:163], v[192:195], v[0:3]
	v_mfma_f32_16x16x32_bf16 v[30:33], v[156:159], v[172:175], v[30:33]
	v_mfma_f32_16x16x32_bf16 v[26:29], v[164:167], v[172:175], v[26:29]
	v_mfma_f32_16x16x32_bf16 v[22:25], v[156:159], v[180:183], v[22:25]
	v_mfma_f32_16x16x32_bf16 v[18:21], v[164:167], v[180:183], v[18:21]
	v_mfma_f32_16x16x32_bf16 v[12:15], v[156:159], v[188:191], v[12:15]
	v_mfma_f32_16x16x32_bf16 v[8:11], v[164:167], v[188:191], v[8:11]
	v_mfma_f32_16x16x32_bf16 v[4:7], v[156:159], v[196:199], v[4:7]
	v_mfma_f32_16x16x32_bf16 v[0:3], v[164:167], v[196:199], v[0:3]
	s_setprio 0
	s_barrier
	s_add_i32 s88, s88, 2
	s_add_u32 s44, s44, 0x100
	s_addc_u32 s45, s45, 0
	s_add_u32 s86, s86, 0x100
	s_addc_u32 s87, s87, 0
	s_cmp_gt_u32 s88, 29
	s_cbranch_scc1 .Lpk_F_exit

.LBB0_786:
	s_ashr_i32 s43, s42, 31
	s_lshl_b64 s[28:29], s[42:43], 20
	s_add_u32 s44, s72, s28
	s_addc_u32 s45, s73, s29
	s_and_b64 s[28:29], s[38:39], exec
	s_cselect_b32 s43, s45, s51
	s_cselect_b32 s91, s44, s50
	s_ashr_i32 s41, s40, 31
	s_lshl_b64 s[28:29], s[40:41], 20
	v_readlane_b32 s41, v255, 14
	s_add_u32 s46, s41, s28
	v_readlane_b32 s28, v255, 15
	s_addc_u32 s47, s28, s29
	s_and_b64 s[28:29], s[38:39], exec
	s_cselect_b32 s41, s47, s53
	s_cselect_b32 vcc_lo, s46, s52
	s_add_u32 s50, s50, 0x80080
	s_addc_u32 s51, s51, 0
	s_add_u32 vcc_hi, s52, 0x100
	v_mov_b32_e32 v0, 0
	s_addc_u32 s92, s53, 0
	s_mov_b32 s93, -2
	v_mov_b32_e32 v1, v0
	v_mov_b32_e32 v2, v0
	v_mov_b32_e32 v3, v0
	v_mov_b32_e32 v4, v0
	v_mov_b32_e32 v5, v0
	v_mov_b32_e32 v6, v0
	v_mov_b32_e32 v7, v0
	v_mov_b32_e32 v12, v0
	v_mov_b32_e32 v13, v0
	v_mov_b32_e32 v14, v0
	v_mov_b32_e32 v15, v0
	v_mov_b32_e32 v22, v0
	v_mov_b32_e32 v23, v0
	v_mov_b32_e32 v24, v0
	v_mov_b32_e32 v25, v0
	v_mov_b32_e32 v30, v0
	v_mov_b32_e32 v31, v0
	v_mov_b32_e32 v32, v0
	v_mov_b32_e32 v33, v0
	v_mov_b32_e32 v38, v0
	v_mov_b32_e32 v39, v0
	v_mov_b32_e32 v40, v0
	v_mov_b32_e32 v41, v0
	v_mov_b32_e32 v46, v0
	v_mov_b32_e32 v47, v0
	v_mov_b32_e32 v48, v0
	v_mov_b32_e32 v49, v0
	v_mov_b32_e32 v54, v0
	v_mov_b32_e32 v55, v0
	v_mov_b32_e32 v56, v0
	v_mov_b32_e32 v57, v0
	v_mov_b32_e32 v8, v0
	v_mov_b32_e32 v9, v0
	v_mov_b32_e32 v10, v0
	v_mov_b32_e32 v11, v0
	v_mov_b32_e32 v18, v0
	v_mov_b32_e32 v19, v0
	v_mov_b32_e32 v20, v0
	v_mov_b32_e32 v21, v0
	v_mov_b32_e32 v26, v0
	v_mov_b32_e32 v27, v0
	v_mov_b32_e32 v28, v0
	v_mov_b32_e32 v29, v0
	v_mov_b32_e32 v34, v0
	v_mov_b32_e32 v35, v0
	v_mov_b32_e32 v36, v0
	v_mov_b32_e32 v37, v0
	v_mov_b32_e32 v42, v0
	v_mov_b32_e32 v43, v0
	v_mov_b32_e32 v44, v0
	v_mov_b32_e32 v45, v0
	v_mov_b32_e32 v50, v0
	v_mov_b32_e32 v51, v0
	v_mov_b32_e32 v52, v0
	v_mov_b32_e32 v53, v0
	v_mov_b32_e32 v58, v0
	v_mov_b32_e32 v59, v0
	v_mov_b32_e32 v60, v0
	v_mov_b32_e32 v61, v0
	v_mov_b32_e32 v62, v0
	v_mov_b32_e32 v63, v0
	v_mov_b32_e32 v64, v0
	v_mov_b32_e32 v65, v0
	v_mov_b32_e32 v66, v0
	v_mov_b32_e32 v67, v0
	v_mov_b32_e32 v68, v0
	v_mov_b32_e32 v69, v0
	v_mov_b32_e32 v70, v0
	v_mov_b32_e32 v71, v0
	v_mov_b32_e32 v72, v0
	v_mov_b32_e32 v73, v0
	v_mov_b32_e32 v78, v0
	v_mov_b32_e32 v79, v0
	v_mov_b32_e32 v80, v0
	v_mov_b32_e32 v81, v0
	v_mov_b32_e32 v86, v0
	v_mov_b32_e32 v87, v0
	v_mov_b32_e32 v88, v0
	v_mov_b32_e32 v89, v0
	v_mov_b32_e32 v94, v0
	v_mov_b32_e32 v95, v0
	v_mov_b32_e32 v96, v0
	v_mov_b32_e32 v97, v0
	v_mov_b32_e32 v102, v0
	v_mov_b32_e32 v103, v0
	v_mov_b32_e32 v104, v0
	v_mov_b32_e32 v105, v0
	v_mov_b32_e32 v110, v0
	v_mov_b32_e32 v111, v0
	v_mov_b32_e32 v112, v0
	v_mov_b32_e32 v113, v0
	v_mov_b32_e32 v118, v0
	v_mov_b32_e32 v119, v0
	v_mov_b32_e32 v120, v0
	v_mov_b32_e32 v121, v0
	v_mov_b32_e32 v74, v0
	v_mov_b32_e32 v75, v0
	v_mov_b32_e32 v76, v0
	v_mov_b32_e32 v77, v0
	v_mov_b32_e32 v82, v0
	v_mov_b32_e32 v83, v0
	v_mov_b32_e32 v84, v0
	v_mov_b32_e32 v85, v0
	v_mov_b32_e32 v90, v0
	v_mov_b32_e32 v91, v0
	v_mov_b32_e32 v92, v0
	v_mov_b32_e32 v93, v0
	v_mov_b32_e32 v98, v0
	v_mov_b32_e32 v99, v0
	v_mov_b32_e32 v100, v0
	v_mov_b32_e32 v101, v0
	v_mov_b32_e32 v106, v0
	v_mov_b32_e32 v107, v0
	v_mov_b32_e32 v108, v0
	v_mov_b32_e32 v109, v0
	v_mov_b32_e32 v114, v0
	v_mov_b32_e32 v115, v0
	v_mov_b32_e32 v116, v0
	v_mov_b32_e32 v117, v0
	v_mov_b32_e32 v122, v0
	v_mov_b32_e32 v123, v0
	v_mov_b32_e32 v124, v0
	v_mov_b32_e32 v125, v0
	v_mov_b32_e32 v126, v0
	v_mov_b32_e32 v127, v0
	v_mov_b32_e32 v128, v0
	v_mov_b32_e32 v129, v0
	s_cmp_eq_u32 s90, 1
	s_cbranch_scc1 .LBB0_787
	s_add_u32 s28, s50, 0xfff80080
	s_addc_u32 s29, s51, -1
	s_add_i32 s94, 0, 0x10000
	s_cmp_eq_u32 s93, 28
	s_cselect_b32 s53, s43, s29
	s_cselect_b32 s52, s91, s28
	s_cselect_b32 s29, s41, s92
	s_cselect_b32 s28, vcc_lo, vcc_hi
	s_add_i32 s96, 0, 0x14000
	s_waitcnt vmcnt(0)
	v_add_u32_e32 v142, s94, v207
	v_add_u32_e32 v158, s96, v207
	ds_read_b128 v[130:133], v142
	ds_read_b128 v[134:137], v142 offset:1024
	ds_read_b128 v[138:141], v142 offset:2048
	ds_read_b128 v[142:145], v142 offset:3072
	ds_read_b128 v[146:149], v158
	ds_read_b128 v[150:153], v158 offset:1024
	ds_read_b128 v[154:157], v158 offset:2048
	ds_read_b128 v[158:161], v158 offset:3072
	v_lshl_add_u64 v[204:205], s[50:51], 0, v[192:193]
	s_add_i32 m0, s59, 0xc000
	ds_read_b128 v[162:165], v224
	ds_read_b128 v[166:169], v224 offset:1024
	ds_read_b128 v[170:173], v224 offset:2048
	ds_read_b128 v[174:177], v224 offset:3072
	ds_read_b128 v[178:181], v224 offset:4096
	ds_read_b128 v[182:185], v224 offset:5120
	ds_read_b128 v[196:199], v224 offset:6144
	ds_read_b128 v[200:203], v224 offset:7168
	global_load_lds_dwordx4 v[204:205], off
	v_lshl_add_u64 v[204:205], s[50:51], 0, v[194:195]
	s_add_i32 m0, s59, 0xe000
	s_nop 0
	global_load_lds_dwordx4 v[204:205], off
	s_waitcnt vmcnt(24)
	s_waitcnt lgkmcnt(0)
	s_barrier
	s_setprio 1
	s_waitcnt lgkmcnt(0)
	v_mfma_f32_16x16x32_bf16 v[126:129], v[130:133], v[162:165], v[126:129]
	v_mfma_f32_16x16x32_bf16 v[122:125], v[138:141], v[162:165], v[122:125]
	v_mfma_f32_16x16x32_bf16 v[114:117], v[130:133], v[170:173], v[114:117]
	v_mfma_f32_16x16x32_bf16 v[106:109], v[138:141], v[170:173], v[106:109]
	v_mfma_f32_16x16x32_bf16 v[98:101], v[130:133], v[178:181], v[98:101]
	v_mfma_f32_16x16x32_bf16 v[90:93], v[138:141], v[178:181], v[90:93]
	v_mfma_f32_16x16x32_bf16 v[82:85], v[130:133], v[196:199], v[82:85]
	v_mfma_f32_16x16x32_bf16 v[74:77], v[138:141], v[196:199], v[74:77]
	v_mfma_f32_16x16x32_bf16 v[126:129], v[134:137], v[166:169], v[126:129]
	v_mfma_f32_16x16x32_bf16 v[122:125], v[142:145], v[166:169], v[122:125]
	v_mfma_f32_16x16x32_bf16 v[114:117], v[134:137], v[174:177], v[114:117]
	v_mfma_f32_16x16x32_bf16 v[106:109], v[142:145], v[174:177], v[106:109]
	v_mfma_f32_16x16x32_bf16 v[98:101], v[134:137], v[182:185], v[98:101]
	v_mfma_f32_16x16x32_bf16 v[90:93], v[142:145], v[182:185], v[90:93]
	v_mfma_f32_16x16x32_bf16 v[82:85], v[134:137], v[200:203], v[82:85]
	v_mfma_f32_16x16x32_bf16 v[74:77], v[142:145], v[200:203], v[74:77]
	s_setprio 0
	s_setprio 1
	v_mfma_f32_16x16x32_bf16 v[118:121], v[146:149], v[162:165], v[118:121]
	v_mfma_f32_16x16x32_bf16 v[110:113], v[154:157], v[162:165], v[110:113]
	v_mfma_f32_16x16x32_bf16 v[102:105], v[146:149], v[170:173], v[102:105]
	v_mfma_f32_16x16x32_bf16 v[94:97], v[154:157], v[170:173], v[94:97]
	v_mfma_f32_16x16x32_bf16 v[86:89], v[146:149], v[178:181], v[86:89]
	v_mfma_f32_16x16x32_bf16 v[78:81], v[154:157], v[178:181], v[78:81]
	v_mfma_f32_16x16x32_bf16 v[70:73], v[146:149], v[196:199], v[70:73]
	v_mfma_f32_16x16x32_bf16 v[66:69], v[154:157], v[196:199], v[66:69]
	v_mfma_f32_16x16x32_bf16 v[118:121], v[150:153], v[166:169], v[118:121]
	v_mfma_f32_16x16x32_bf16 v[110:113], v[158:161], v[166:169], v[110:113]
	v_mfma_f32_16x16x32_bf16 v[102:105], v[150:153], v[174:177], v[102:105]
	v_mfma_f32_16x16x32_bf16 v[94:97], v[158:161], v[174:177], v[94:97]
	v_mfma_f32_16x16x32_bf16 v[86:89], v[150:153], v[182:185], v[86:89]
	v_mfma_f32_16x16x32_bf16 v[78:81], v[158:161], v[182:185], v[78:81]
	v_mfma_f32_16x16x32_bf16 v[70:73], v[150:153], v[200:203], v[70:73]
	v_mfma_f32_16x16x32_bf16 v[66:69], v[158:161], v[200:203], v[66:69]
	s_setprio 0
	s_barrier
	s_add_i32 s94, s94, s37
	v_lshl_add_u64 v[204:205], s[28:29], 0, v[16:17]
	s_mov_b32 m0, s94
	ds_read_b128 v[162:165], v224 offset:16384
	ds_read_b128 v[166:169], v224 offset:17408
	ds_read_b128 v[170:173], v224 offset:18432
	ds_read_b128 v[174:177], v224 offset:19456
	ds_read_b128 v[178:181], v224 offset:20480
	ds_read_b128 v[182:185], v224 offset:21504
	ds_read_b128 v[196:199], v224 offset:22528
	ds_read_b128 v[200:203], v224 offset:23552
	global_load_lds_dwordx4 v[204:205], off
	s_add_i32 m0, s94, 0x2000
	s_add_u32 s94, s28, 0x80000
	v_lshl_add_u64 v[226:227], s[28:29], 0, v[186:187]
	s_addc_u32 s95, s29, 0
	s_add_i32 s96, s96, s37
	global_load_lds_dwordx4 v[226:227], off
	v_lshl_add_u64 v[228:229], s[94:95], 0, v[16:17]
	s_mov_b32 m0, s96
	v_lshl_add_u64 v[230:231], s[52:53], 0, v[188:189]
	global_load_lds_dwordx4 v[228:229], off
	v_lshl_add_u64 v[228:229], s[94:95], 0, v[186:187]
	s_add_i32 m0, s96, 0x2000
	s_nop 0
	global_load_lds_dwordx4 v[228:229], off
	v_lshl_add_u64 v[228:229], s[52:53], 0, v[190:191]
	s_mov_b32 m0, s59
	s_nop 0
	global_load_lds_dwordx4 v[228:229], off
	s_mov_b32 m0, s83
	s_nop 0
	global_load_lds_dwordx4 v[230:231], off
	s_waitcnt vmcnt(24)
	s_waitcnt lgkmcnt(0)
	s_barrier
	s_setprio 1
	s_waitcnt lgkmcnt(0)
	v_mfma_f32_16x16x32_bf16 v[62:65], v[130:133], v[162:165], v[62:65]
	v_mfma_f32_16x16x32_bf16 v[58:61], v[138:141], v[162:165], v[58:61]
	v_mfma_f32_16x16x32_bf16 v[50:53], v[130:133], v[170:173], v[50:53]
	v_mfma_f32_16x16x32_bf16 v[42:45], v[138:141], v[170:173], v[42:45]
	v_mfma_f32_16x16x32_bf16 v[34:37], v[130:133], v[178:181], v[34:37]
	v_mfma_f32_16x16x32_bf16 v[26:29], v[138:141], v[178:181], v[26:29]
	v_mfma_f32_16x16x32_bf16 v[18:21], v[130:133], v[196:199], v[18:21]
	v_mfma_f32_16x16x32_bf16 v[8:11], v[138:141], v[196:199], v[8:11]
	v_mfma_f32_16x16x32_bf16 v[62:65], v[134:137], v[166:169], v[62:65]
	v_mfma_f32_16x16x32_bf16 v[58:61], v[142:145], v[166:169], v[58:61]
	v_mfma_f32_16x16x32_bf16 v[50:53], v[134:137], v[174:177], v[50:53]
	v_mfma_f32_16x16x32_bf16 v[42:45], v[142:145], v[174:177], v[42:45]
	v_mfma_f32_16x16x32_bf16 v[34:37], v[134:137], v[182:185], v[34:37]
	v_mfma_f32_16x16x32_bf16 v[26:29], v[142:145], v[182:185], v[26:29]
	v_mfma_f32_16x16x32_bf16 v[18:21], v[134:137], v[200:203], v[18:21]
	v_mfma_f32_16x16x32_bf16 v[8:11], v[142:145], v[200:203], v[8:11]
	s_setprio 0
	s_setprio 1
	v_mfma_f32_16x16x32_bf16 v[54:57], v[146:149], v[162:165], v[54:57]
	v_mfma_f32_16x16x32_bf16 v[46:49], v[154:157], v[162:165], v[46:49]
	v_mfma_f32_16x16x32_bf16 v[38:41], v[146:149], v[170:173], v[38:41]
	v_mfma_f32_16x16x32_bf16 v[30:33], v[154:157], v[170:173], v[30:33]
	v_mfma_f32_16x16x32_bf16 v[22:25], v[146:149], v[178:181], v[22:25]
	v_mfma_f32_16x16x32_bf16 v[12:15], v[154:157], v[178:181], v[12:15]
	v_mfma_f32_16x16x32_bf16 v[4:7], v[146:149], v[196:199], v[4:7]
	v_mfma_f32_16x16x32_bf16 v[0:3], v[154:157], v[196:199], v[0:3]
	v_mfma_f32_16x16x32_bf16 v[54:57], v[150:153], v[166:169], v[54:57]
	v_mfma_f32_16x16x32_bf16 v[46:49], v[158:161], v[166:169], v[46:49]
	v_mfma_f32_16x16x32_bf16 v[38:41], v[150:153], v[174:177], v[38:41]
	v_mfma_f32_16x16x32_bf16 v[30:33], v[158:161], v[174:177], v[30:33]
	v_mfma_f32_16x16x32_bf16 v[22:25], v[150:153], v[182:185], v[22:25]
	v_mfma_f32_16x16x32_bf16 v[12:15], v[158:161], v[182:185], v[12:15]
	v_mfma_f32_16x16x32_bf16 v[4:7], v[150:153], v[200:203], v[4:7]
	v_mfma_f32_16x16x32_bf16 v[0:3], v[158:161], v[200:203], v[0:3]
	s_setprio 0
	s_barrier
	s_add_i32 s94, 0, 0x18000
	s_add_i32 s95, 0, 0x1c000
	v_add_u32_e32 v142, s94, v207
	v_add_u32_e32 v158, s95, v207
	ds_read_b128 v[130:133], v142
	ds_read_b128 v[134:137], v142 offset:1024
	ds_read_b128 v[138:141], v142 offset:2048
	ds_read_b128 v[142:145], v142 offset:3072
	ds_read_b128 v[146:149], v158
	ds_read_b128 v[150:153], v158 offset:1024
	ds_read_b128 v[154:157], v158 offset:2048
	ds_read_b128 v[158:161], v158 offset:3072
	s_add_u32 s52, s52, 0x80000
	s_addc_u32 s53, s53, 0
	s_mov_b32 m0, s84
	v_lshl_add_u64 v[232:233], s[52:53], 0, v[190:191]
	ds_read_b128 v[162:165], v224 offset:32768
	ds_read_b128 v[166:169], v224 offset:33792
	ds_read_b128 v[170:173], v224 offset:34816
	ds_read_b128 v[174:177], v224 offset:35840
	ds_read_b128 v[178:181], v224 offset:36864
	ds_read_b128 v[182:185], v224 offset:37888
	ds_read_b128 v[196:199], v224 offset:38912
	ds_read_b128 v[200:203], v224 offset:39936
	global_load_lds_dwordx4 v[232:233], off
	v_lshl_add_u64 v[232:233], s[52:53], 0, v[188:189]
	s_mov_b32 m0, s85
	s_nop 0
	global_load_lds_dwordx4 v[232:233], off
	s_waitcnt vmcnt(8)
	s_waitcnt lgkmcnt(0)
	s_barrier
	s_setprio 1
	s_waitcnt lgkmcnt(0)
	v_mfma_f32_16x16x32_bf16 v[126:129], v[130:133], v[162:165], v[126:129]
	v_mfma_f32_16x16x32_bf16 v[122:125], v[138:141], v[162:165], v[122:125]
	v_mfma_f32_16x16x32_bf16 v[114:117], v[130:133], v[170:173], v[114:117]
	v_mfma_f32_16x16x32_bf16 v[106:109], v[138:141], v[170:173], v[106:109]
	v_mfma_f32_16x16x32_bf16 v[98:101], v[130:133], v[178:181], v[98:101]
	v_mfma_f32_16x16x32_bf16 v[90:93], v[138:141], v[178:181], v[90:93]
	v_mfma_f32_16x16x32_bf16 v[82:85], v[130:133], v[196:199], v[82:85]
	v_mfma_f32_16x16x32_bf16 v[74:77], v[138:141], v[196:199], v[74:77]
	v_mfma_f32_16x16x32_bf16 v[126:129], v[134:137], v[166:169], v[126:129]
	v_mfma_f32_16x16x32_bf16 v[122:125], v[142:145], v[166:169], v[122:125]
	v_mfma_f32_16x16x32_bf16 v[114:117], v[134:137], v[174:177], v[114:117]
	v_mfma_f32_16x16x32_bf16 v[106:109], v[142:145], v[174:177], v[106:109]
	v_mfma_f32_16x16x32_bf16 v[98:101], v[134:137], v[182:185], v[98:101]
	v_mfma_f32_16x16x32_bf16 v[90:93], v[142:145], v[182:185], v[90:93]
	v_mfma_f32_16x16x32_bf16 v[82:85], v[134:137], v[200:203], v[82:85]
	v_mfma_f32_16x16x32_bf16 v[74:77], v[142:145], v[200:203], v[74:77]
	s_setprio 0
	s_setprio 1
	v_mfma_f32_16x16x32_bf16 v[118:121], v[146:149], v[162:165], v[118:121]
	v_mfma_f32_16x16x32_bf16 v[110:113], v[154:157], v[162:165], v[110:113]
	v_mfma_f32_16x16x32_bf16 v[102:105], v[146:149], v[170:173], v[102:105]
	v_mfma_f32_16x16x32_bf16 v[94:97], v[154:157], v[170:173], v[94:97]
	v_mfma_f32_16x16x32_bf16 v[86:89], v[146:149], v[178:181], v[86:89]
	v_mfma_f32_16x16x32_bf16 v[78:81], v[154:157], v[178:181], v[78:81]
	v_mfma_f32_16x16x32_bf16 v[70:73], v[146:149], v[196:199], v[70:73]
	v_mfma_f32_16x16x32_bf16 v[66:69], v[154:157], v[196:199], v[66:69]
	v_mfma_f32_16x16x32_bf16 v[118:121], v[150:153], v[166:169], v[118:121]
	v_mfma_f32_16x16x32_bf16 v[110:113], v[158:161], v[166:169], v[110:113]
	v_mfma_f32_16x16x32_bf16 v[102:105], v[150:153], v[174:177], v[102:105]
	v_mfma_f32_16x16x32_bf16 v[94:97], v[158:161], v[174:177], v[94:97]
	v_mfma_f32_16x16x32_bf16 v[86:89], v[150:153], v[182:185], v[86:89]
	v_mfma_f32_16x16x32_bf16 v[78:81], v[158:161], v[182:185], v[78:81]
	v_mfma_f32_16x16x32_bf16 v[70:73], v[150:153], v[200:203], v[70:73]
	v_mfma_f32_16x16x32_bf16 v[66:69], v[158:161], v[200:203], v[66:69]
	s_setprio 0
	s_barrier
	s_add_i32 s52, s94, s37
	v_lshl_add_u64 v[204:205], v[204:205], 0, s[34:35]
	s_mov_b32 m0, s52
	ds_read_b128 v[162:165], v224 offset:49152
	ds_read_b128 v[166:169], v224 offset:50176
	ds_read_b128 v[170:173], v224 offset:51200
	ds_read_b128 v[174:177], v224 offset:52224
	ds_read_b128 v[178:181], v224 offset:53248
	ds_read_b128 v[182:185], v224 offset:54272
	ds_read_b128 v[196:199], v224 offset:55296
	ds_read_b128 v[200:203], v224 offset:56320
	global_load_lds_dwordx4 v[204:205], off
	s_add_i32 m0, s52, 0x2000
	s_add_u32 s28, s28, 0x80080
	v_lshl_add_u64 v[204:205], v[226:227], 0, s[34:35]
	s_addc_u32 s29, s29, 0
	s_add_i32 s52, s95, s37
	global_load_lds_dwordx4 v[204:205], off
	v_lshl_add_u64 v[204:205], s[28:29], 0, v[16:17]
	s_mov_b32 m0, s52
	s_nop 0
	global_load_lds_dwordx4 v[204:205], off
	v_lshl_add_u64 v[204:205], s[28:29], 0, v[186:187]
	s_add_i32 m0, s52, 0x2000
	s_nop 0
	global_load_lds_dwordx4 v[204:205], off
	v_lshl_add_u64 v[204:205], v[228:229], 0, s[34:35]
	s_mov_b32 m0, s88
	s_nop 0
	global_load_lds_dwordx4 v[204:205], off
	v_lshl_add_u64 v[204:205], v[230:231], 0, s[34:35]
	s_mov_b32 m0, s89
	s_nop 0
	global_load_lds_dwordx4 v[204:205], off
	s_waitcnt vmcnt(8)
	s_waitcnt lgkmcnt(0)
	s_barrier
	s_setprio 1
	s_waitcnt lgkmcnt(0)
	v_mfma_f32_16x16x32_bf16 v[62:65], v[130:133], v[162:165], v[62:65]
	v_mfma_f32_16x16x32_bf16 v[58:61], v[138:141], v[162:165], v[58:61]
	v_mfma_f32_16x16x32_bf16 v[50:53], v[130:133], v[170:173], v[50:53]
	v_mfma_f32_16x16x32_bf16 v[42:45], v[138:141], v[170:173], v[42:45]
	v_mfma_f32_16x16x32_bf16 v[34:37], v[130:133], v[178:181], v[34:37]
	v_mfma_f32_16x16x32_bf16 v[26:29], v[138:141], v[178:181], v[26:29]
	v_mfma_f32_16x16x32_bf16 v[18:21], v[130:133], v[196:199], v[18:21]
	v_mfma_f32_16x16x32_bf16 v[8:11], v[138:141], v[196:199], v[8:11]
	v_mfma_f32_16x16x32_bf16 v[62:65], v[134:137], v[166:169], v[62:65]
	v_mfma_f32_16x16x32_bf16 v[58:61], v[142:145], v[166:169], v[58:61]
	v_mfma_f32_16x16x32_bf16 v[50:53], v[134:137], v[174:177], v[50:53]
	v_mfma_f32_16x16x32_bf16 v[42:45], v[142:145], v[174:177], v[42:45]
	v_mfma_f32_16x16x32_bf16 v[34:37], v[134:137], v[182:185], v[34:37]
	v_mfma_f32_16x16x32_bf16 v[26:29], v[142:145], v[182:185], v[26:29]
	v_mfma_f32_16x16x32_bf16 v[18:21], v[134:137], v[200:203], v[18:21]
	v_mfma_f32_16x16x32_bf16 v[8:11], v[142:145], v[200:203], v[8:11]
	s_setprio 0
	s_setprio 1
	v_mfma_f32_16x16x32_bf16 v[54:57], v[146:149], v[162:165], v[54:57]
	v_mfma_f32_16x16x32_bf16 v[46:49], v[154:157], v[162:165], v[46:49]
	v_mfma_f32_16x16x32_bf16 v[38:41], v[146:149], v[170:173], v[38:41]
	v_mfma_f32_16x16x32_bf16 v[30:33], v[154:157], v[170:173], v[30:33]
	v_mfma_f32_16x16x32_bf16 v[22:25], v[146:149], v[178:181], v[22:25]
	v_mfma_f32_16x16x32_bf16 v[12:15], v[154:157], v[178:181], v[12:15]
	v_mfma_f32_16x16x32_bf16 v[4:7], v[146:149], v[196:199], v[4:7]
	v_mfma_f32_16x16x32_bf16 v[0:3], v[154:157], v[196:199], v[0:3]
	v_mfma_f32_16x16x32_bf16 v[54:57], v[150:153], v[166:169], v[54:57]
	v_mfma_f32_16x16x32_bf16 v[46:49], v[158:161], v[166:169], v[46:49]
	v_mfma_f32_16x16x32_bf16 v[38:41], v[150:153], v[174:177], v[38:41]
	v_mfma_f32_16x16x32_bf16 v[30:33], v[158:161], v[174:177], v[30:33]
	v_mfma_f32_16x16x32_bf16 v[22:25], v[150:153], v[182:185], v[22:25]
	v_mfma_f32_16x16x32_bf16 v[12:15], v[158:161], v[182:185], v[12:15]
	v_mfma_f32_16x16x32_bf16 v[4:7], v[150:153], v[200:203], v[4:7]
	v_mfma_f32_16x16x32_bf16 v[0:3], v[158:161], v[200:203], v[0:3]
	s_setprio 0
	s_barrier
	s_add_i32 s93, s93, 2
	s_add_u32 s50, s50, 0x100
	s_addc_u32 s51, s51, 0
	s_add_u32 vcc_hi, vcc_hi, 0x100
	s_addc_u32 s92, s92, 0
	s_cmp_gt_u32 s93, 29
	s_cbranch_scc1 .Lpk_G_exit

.LBB0_919:
	s_ashr_i32 s27, s26, 31
	s_lshl_b64 s[28:29], s[26:27], 20
	s_add_u32 s40, s68, s28
	s_addc_u32 s41, s69, s29
	s_and_b64 s[28:29], s[38:39], exec
	s_cselect_b32 s27, s41, s47
	s_cselect_b32 s86, s40, s46
	s_ashr_i32 s23, s22, 31
	s_lshl_b64 s[28:29], s[22:23], 20
	v_readlane_b32 s23, v255, 16
	s_add_u32 s42, s23, s28
	v_readlane_b32 s23, v255, 17
	s_addc_u32 s43, s23, s29
	s_and_b64 s[28:29], s[38:39], exec
	s_cselect_b32 s23, s43, s49
	s_cselect_b32 s87, s42, s48
	s_add_u32 s46, s46, 0x80080
	s_addc_u32 s47, s47, 0
	s_add_u32 s88, s48, 0x100
	v_mov_b32_e32 v0, 0
	s_addc_u32 s89, s49, 0
	s_mov_b32 s90, -2
	v_mov_b32_e32 v1, v0
	v_mov_b32_e32 v2, v0
	v_mov_b32_e32 v3, v0
	v_mov_b32_e32 v8, v0
	v_mov_b32_e32 v9, v0
	v_mov_b32_e32 v10, v0
	v_mov_b32_e32 v11, v0
	v_mov_b32_e32 v18, v0
	v_mov_b32_e32 v19, v0
	v_mov_b32_e32 v20, v0
	v_mov_b32_e32 v21, v0
	v_mov_b32_e32 v26, v0
	v_mov_b32_e32 v27, v0
	v_mov_b32_e32 v28, v0
	v_mov_b32_e32 v29, v0
	v_mov_b32_e32 v34, v0
	v_mov_b32_e32 v35, v0
	v_mov_b32_e32 v36, v0
	v_mov_b32_e32 v37, v0
	v_mov_b32_e32 v42, v0
	v_mov_b32_e32 v43, v0
	v_mov_b32_e32 v44, v0
	v_mov_b32_e32 v45, v0
	v_mov_b32_e32 v50, v0
	v_mov_b32_e32 v51, v0
	v_mov_b32_e32 v52, v0
	v_mov_b32_e32 v53, v0
	v_mov_b32_e32 v58, v0
	v_mov_b32_e32 v59, v0
	v_mov_b32_e32 v60, v0
	v_mov_b32_e32 v61, v0
	v_mov_b32_e32 v4, v0
	v_mov_b32_e32 v5, v0
	v_mov_b32_e32 v6, v0
	v_mov_b32_e32 v7, v0
	v_mov_b32_e32 v12, v0
	v_mov_b32_e32 v13, v0
	v_mov_b32_e32 v14, v0
	v_mov_b32_e32 v15, v0
	v_mov_b32_e32 v22, v0
	v_mov_b32_e32 v23, v0
	v_mov_b32_e32 v24, v0
	v_mov_b32_e32 v25, v0
	v_mov_b32_e32 v30, v0
	v_mov_b32_e32 v31, v0
	v_mov_b32_e32 v32, v0
	v_mov_b32_e32 v33, v0
	v_mov_b32_e32 v38, v0
	v_mov_b32_e32 v39, v0
	v_mov_b32_e32 v40, v0
	v_mov_b32_e32 v41, v0
	v_mov_b32_e32 v46, v0
	v_mov_b32_e32 v47, v0
	v_mov_b32_e32 v48, v0
	v_mov_b32_e32 v49, v0
	v_mov_b32_e32 v54, v0
	v_mov_b32_e32 v55, v0
	v_mov_b32_e32 v56, v0
	v_mov_b32_e32 v57, v0
	v_mov_b32_e32 v62, v0
	v_mov_b32_e32 v63, v0
	v_mov_b32_e32 v64, v0
	v_mov_b32_e32 v65, v0
	v_mov_b32_e32 v66, v0
	v_mov_b32_e32 v67, v0
	v_mov_b32_e32 v68, v0
	v_mov_b32_e32 v69, v0
	v_mov_b32_e32 v74, v0
	v_mov_b32_e32 v75, v0
	v_mov_b32_e32 v76, v0
	v_mov_b32_e32 v77, v0
	v_mov_b32_e32 v82, v0
	v_mov_b32_e32 v83, v0
	v_mov_b32_e32 v84, v0
	v_mov_b32_e32 v85, v0
	v_mov_b32_e32 v90, v0
	v_mov_b32_e32 v91, v0
	v_mov_b32_e32 v92, v0
	v_mov_b32_e32 v93, v0
	v_mov_b32_e32 v98, v0
	v_mov_b32_e32 v99, v0
	v_mov_b32_e32 v100, v0
	v_mov_b32_e32 v101, v0
	v_mov_b32_e32 v106, v0
	v_mov_b32_e32 v107, v0
	v_mov_b32_e32 v108, v0
	v_mov_b32_e32 v109, v0
	v_mov_b32_e32 v114, v0
	v_mov_b32_e32 v115, v0
	v_mov_b32_e32 v116, v0
	v_mov_b32_e32 v117, v0
	v_mov_b32_e32 v122, v0
	v_mov_b32_e32 v123, v0
	v_mov_b32_e32 v124, v0
	v_mov_b32_e32 v125, v0
	v_mov_b32_e32 v70, v0
	v_mov_b32_e32 v71, v0
	v_mov_b32_e32 v72, v0
	v_mov_b32_e32 v73, v0
	v_mov_b32_e32 v78, v0
	v_mov_b32_e32 v79, v0
	v_mov_b32_e32 v80, v0
	v_mov_b32_e32 v81, v0
	v_mov_b32_e32 v86, v0
	v_mov_b32_e32 v87, v0
	v_mov_b32_e32 v88, v0
	v_mov_b32_e32 v89, v0
	v_mov_b32_e32 v94, v0
	v_mov_b32_e32 v95, v0
	v_mov_b32_e32 v96, v0
	v_mov_b32_e32 v97, v0
	v_mov_b32_e32 v102, v0
	v_mov_b32_e32 v103, v0
	v_mov_b32_e32 v104, v0
	v_mov_b32_e32 v105, v0
	v_mov_b32_e32 v110, v0
	v_mov_b32_e32 v111, v0
	v_mov_b32_e32 v112, v0
	v_mov_b32_e32 v113, v0
	v_mov_b32_e32 v118, v0
	v_mov_b32_e32 v119, v0
	v_mov_b32_e32 v120, v0
	v_mov_b32_e32 v121, v0
	v_mov_b32_e32 v126, v0
	v_mov_b32_e32 v127, v0
	v_mov_b32_e32 v128, v0
	v_mov_b32_e32 v129, v0
	s_cmp_eq_u32 s84, 1
	s_cbranch_scc1 .LBB0_920
	s_add_u32 s28, s46, 0xfff80080
	s_addc_u32 s29, s47, -1
	s_add_i32 s91, 0, 0x10000
	s_cmp_eq_u32 s90, 28
	s_cselect_b32 s49, s27, s29
	s_cselect_b32 s48, s86, s28
	s_cselect_b32 s29, s23, s89
	s_cselect_b32 s28, s87, s88
	s_add_i32 s94, 0, 0x14000
	v_add_u32_e32 v156, s91, v141
	v_add_u32_e32 v172, s94, v141
	ds_read_b128 v[144:147], v156
	ds_read_b128 v[148:151], v156 offset:1024
	ds_read_b128 v[152:155], v156 offset:2048
	ds_read_b128 v[156:159], v156 offset:3072
	ds_read_b128 v[160:163], v172
	ds_read_b128 v[164:167], v172 offset:1024
	ds_read_b128 v[168:171], v172 offset:2048
	ds_read_b128 v[172:175], v172 offset:3072
	v_lshl_add_u64 v[216:217], s[46:47], 0, v[136:137]
	s_add_i32 m0, s45, 0xc000
	ds_read_b128 v[176:179], v143
	ds_read_b128 v[180:183], v143 offset:1024
	ds_read_b128 v[184:187], v143 offset:2048
	ds_read_b128 v[188:191], v143 offset:3072
	ds_read_b128 v[192:195], v143 offset:4096
	ds_read_b128 v[196:199], v143 offset:5120
	ds_read_b128 v[200:203], v143 offset:6144
	ds_read_b128 v[204:207], v143 offset:7168
	global_load_lds_dwordx4 v[216:217], off
	v_lshl_add_u64 v[216:217], s[46:47], 0, v[138:139]
	s_add_i32 m0, s45, 0xe000
	s_nop 0
	global_load_lds_dwordx4 v[216:217], off
	s_waitcnt vmcnt(16)
	s_waitcnt lgkmcnt(0)
	s_barrier
	s_setprio 1
	s_waitcnt lgkmcnt(0)
	v_mfma_f32_16x16x32_bf16 v[126:129], v[144:147], v[176:179], v[126:129]
	v_mfma_f32_16x16x32_bf16 v[118:121], v[152:155], v[176:179], v[118:121]
	v_mfma_f32_16x16x32_bf16 v[110:113], v[144:147], v[184:187], v[110:113]
	v_mfma_f32_16x16x32_bf16 v[102:105], v[152:155], v[184:187], v[102:105]
	v_mfma_f32_16x16x32_bf16 v[94:97], v[144:147], v[192:195], v[94:97]
	v_mfma_f32_16x16x32_bf16 v[86:89], v[152:155], v[192:195], v[86:89]
	v_mfma_f32_16x16x32_bf16 v[78:81], v[144:147], v[200:203], v[78:81]
	v_mfma_f32_16x16x32_bf16 v[70:73], v[152:155], v[200:203], v[70:73]
	v_mfma_f32_16x16x32_bf16 v[126:129], v[148:151], v[180:183], v[126:129]
	v_mfma_f32_16x16x32_bf16 v[118:121], v[156:159], v[180:183], v[118:121]
	v_mfma_f32_16x16x32_bf16 v[110:113], v[148:151], v[188:191], v[110:113]
	v_mfma_f32_16x16x32_bf16 v[102:105], v[156:159], v[188:191], v[102:105]
	v_mfma_f32_16x16x32_bf16 v[94:97], v[148:151], v[196:199], v[94:97]
	v_mfma_f32_16x16x32_bf16 v[86:89], v[156:159], v[196:199], v[86:89]
	v_mfma_f32_16x16x32_bf16 v[78:81], v[148:151], v[204:207], v[78:81]
	v_mfma_f32_16x16x32_bf16 v[70:73], v[156:159], v[204:207], v[70:73]
	s_setprio 0
	s_setprio 1
	v_mfma_f32_16x16x32_bf16 v[122:125], v[160:163], v[176:179], v[122:125]
	v_mfma_f32_16x16x32_bf16 v[114:117], v[168:171], v[176:179], v[114:117]
	v_mfma_f32_16x16x32_bf16 v[106:109], v[160:163], v[184:187], v[106:109]
	v_mfma_f32_16x16x32_bf16 v[98:101], v[168:171], v[184:187], v[98:101]
	v_mfma_f32_16x16x32_bf16 v[90:93], v[160:163], v[192:195], v[90:93]
	v_mfma_f32_16x16x32_bf16 v[82:85], v[168:171], v[192:195], v[82:85]
	v_mfma_f32_16x16x32_bf16 v[74:77], v[160:163], v[200:203], v[74:77]
	v_mfma_f32_16x16x32_bf16 v[66:69], v[168:171], v[200:203], v[66:69]
	v_mfma_f32_16x16x32_bf16 v[122:125], v[164:167], v[180:183], v[122:125]
	v_mfma_f32_16x16x32_bf16 v[114:117], v[172:175], v[180:183], v[114:117]
	v_mfma_f32_16x16x32_bf16 v[106:109], v[164:167], v[188:191], v[106:109]
	v_mfma_f32_16x16x32_bf16 v[98:101], v[172:175], v[188:191], v[98:101]
	v_mfma_f32_16x16x32_bf16 v[90:93], v[164:167], v[196:199], v[90:93]
	v_mfma_f32_16x16x32_bf16 v[82:85], v[172:175], v[196:199], v[82:85]
	v_mfma_f32_16x16x32_bf16 v[74:77], v[164:167], v[204:207], v[74:77]
	v_mfma_f32_16x16x32_bf16 v[66:69], v[172:175], v[204:207], v[66:69]
	s_setprio 0
	s_barrier
	s_add_i32 s91, s91, s37
	v_lshl_add_u64 v[216:217], s[28:29], 0, v[16:17]
	s_mov_b32 m0, s91
	ds_read_b128 v[176:179], v143 offset:16384
	ds_read_b128 v[180:183], v143 offset:17408
	ds_read_b128 v[184:187], v143 offset:18432
	ds_read_b128 v[188:191], v143 offset:19456
	ds_read_b128 v[192:195], v143 offset:20480
	ds_read_b128 v[196:199], v143 offset:21504
	ds_read_b128 v[200:203], v143 offset:22528
	ds_read_b128 v[204:207], v143 offset:23552
	global_load_lds_dwordx4 v[216:217], off
	s_add_i32 m0, s91, 0x2000
	s_add_u32 s92, s28, 0x80000
	v_lshl_add_u64 v[224:225], s[28:29], 0, v[130:131]
	s_addc_u32 s93, s29, 0
	s_add_i32 s91, s94, s37
	global_load_lds_dwordx4 v[224:225], off
	v_lshl_add_u64 v[226:227], s[92:93], 0, v[16:17]
	s_mov_b32 m0, s91
	v_lshl_add_u64 v[228:229], s[48:49], 0, v[132:133]
	global_load_lds_dwordx4 v[226:227], off
	v_lshl_add_u64 v[226:227], s[92:93], 0, v[130:131]
	s_add_i32 m0, s91, 0x2000
	s_nop 0
	global_load_lds_dwordx4 v[226:227], off
	v_lshl_add_u64 v[226:227], s[48:49], 0, v[134:135]
	s_mov_b32 m0, s45
	s_nop 0
	global_load_lds_dwordx4 v[226:227], off
	s_mov_b32 m0, s53
	s_nop 0
	global_load_lds_dwordx4 v[228:229], off
	s_waitcnt vmcnt(16)
	s_waitcnt lgkmcnt(0)
	s_barrier
	s_setprio 1
	s_waitcnt lgkmcnt(0)
	v_mfma_f32_16x16x32_bf16 v[62:65], v[144:147], v[176:179], v[62:65]
	v_mfma_f32_16x16x32_bf16 v[54:57], v[152:155], v[176:179], v[54:57]
	v_mfma_f32_16x16x32_bf16 v[46:49], v[144:147], v[184:187], v[46:49]
	v_mfma_f32_16x16x32_bf16 v[38:41], v[152:155], v[184:187], v[38:41]
	v_mfma_f32_16x16x32_bf16 v[30:33], v[144:147], v[192:195], v[30:33]
	v_mfma_f32_16x16x32_bf16 v[22:25], v[152:155], v[192:195], v[22:25]
	v_mfma_f32_16x16x32_bf16 v[12:15], v[144:147], v[200:203], v[12:15]
	v_mfma_f32_16x16x32_bf16 v[4:7], v[152:155], v[200:203], v[4:7]
	v_mfma_f32_16x16x32_bf16 v[62:65], v[148:151], v[180:183], v[62:65]
	v_mfma_f32_16x16x32_bf16 v[54:57], v[156:159], v[180:183], v[54:57]
	v_mfma_f32_16x16x32_bf16 v[46:49], v[148:151], v[188:191], v[46:49]
	v_mfma_f32_16x16x32_bf16 v[38:41], v[156:159], v[188:191], v[38:41]
	v_mfma_f32_16x16x32_bf16 v[30:33], v[148:151], v[196:199], v[30:33]
	v_mfma_f32_16x16x32_bf16 v[22:25], v[156:159], v[196:199], v[22:25]
	v_mfma_f32_16x16x32_bf16 v[12:15], v[148:151], v[204:207], v[12:15]
	v_mfma_f32_16x16x32_bf16 v[4:7], v[156:159], v[204:207], v[4:7]
	s_setprio 0
	s_setprio 1
	v_mfma_f32_16x16x32_bf16 v[58:61], v[160:163], v[176:179], v[58:61]
	v_mfma_f32_16x16x32_bf16 v[50:53], v[168:171], v[176:179], v[50:53]
	v_mfma_f32_16x16x32_bf16 v[42:45], v[160:163], v[184:187], v[42:45]
	v_mfma_f32_16x16x32_bf16 v[34:37], v[168:171], v[184:187], v[34:37]
	v_mfma_f32_16x16x32_bf16 v[26:29], v[160:163], v[192:195], v[26:29]
	v_mfma_f32_16x16x32_bf16 v[18:21], v[168:171], v[192:195], v[18:21]
	v_mfma_f32_16x16x32_bf16 v[8:11], v[160:163], v[200:203], v[8:11]
	v_mfma_f32_16x16x32_bf16 v[0:3], v[168:171], v[200:203], v[0:3]
	v_mfma_f32_16x16x32_bf16 v[58:61], v[164:167], v[180:183], v[58:61]
	v_mfma_f32_16x16x32_bf16 v[50:53], v[172:175], v[180:183], v[50:53]
	v_mfma_f32_16x16x32_bf16 v[42:45], v[164:167], v[188:191], v[42:45]
	v_mfma_f32_16x16x32_bf16 v[34:37], v[172:175], v[188:191], v[34:37]
	v_mfma_f32_16x16x32_bf16 v[26:29], v[164:167], v[196:199], v[26:29]
	v_mfma_f32_16x16x32_bf16 v[18:21], v[172:175], v[196:199], v[18:21]
	v_mfma_f32_16x16x32_bf16 v[8:11], v[164:167], v[204:207], v[8:11]
	v_mfma_f32_16x16x32_bf16 v[0:3], v[172:175], v[204:207], v[0:3]
	s_setprio 0
	s_barrier
	s_add_i32 s91, 0, 0x18000
	s_add_i32 s92, 0, 0x1c000
	v_add_u32_e32 v156, s91, v141
	v_add_u32_e32 v172, s92, v141
	ds_read_b128 v[144:147], v156
	ds_read_b128 v[148:151], v156 offset:1024
	ds_read_b128 v[152:155], v156 offset:2048
	ds_read_b128 v[156:159], v156 offset:3072
	ds_read_b128 v[160:163], v172
	ds_read_b128 v[164:167], v172 offset:1024
	ds_read_b128 v[168:171], v172 offset:2048
	ds_read_b128 v[172:175], v172 offset:3072
	s_add_u32 s48, s48, 0x80000
	s_addc_u32 s49, s49, 0
	s_mov_b32 m0, s57
	v_lshl_add_u64 v[230:231], s[48:49], 0, v[134:135]
	ds_read_b128 v[176:179], v143 offset:32768
	ds_read_b128 v[180:183], v143 offset:33792
	ds_read_b128 v[184:187], v143 offset:34816
	ds_read_b128 v[188:191], v143 offset:35840
	ds_read_b128 v[192:195], v143 offset:36864
	ds_read_b128 v[196:199], v143 offset:37888
	ds_read_b128 v[200:203], v143 offset:38912
	ds_read_b128 v[204:207], v143 offset:39936
	global_load_lds_dwordx4 v[230:231], off
	v_lshl_add_u64 v[230:231], s[48:49], 0, v[132:133]
	s_mov_b32 m0, s58
	s_nop 0
	global_load_lds_dwordx4 v[230:231], off
	s_waitcnt vmcnt(8)
	s_waitcnt lgkmcnt(0)
	s_barrier
	s_setprio 1
	s_waitcnt lgkmcnt(0)
	v_mfma_f32_16x16x32_bf16 v[126:129], v[144:147], v[176:179], v[126:129]
	v_mfma_f32_16x16x32_bf16 v[118:121], v[152:155], v[176:179], v[118:121]
	v_mfma_f32_16x16x32_bf16 v[110:113], v[144:147], v[184:187], v[110:113]
	v_mfma_f32_16x16x32_bf16 v[102:105], v[152:155], v[184:187], v[102:105]
	v_mfma_f32_16x16x32_bf16 v[94:97], v[144:147], v[192:195], v[94:97]
	v_mfma_f32_16x16x32_bf16 v[86:89], v[152:155], v[192:195], v[86:89]
	v_mfma_f32_16x16x32_bf16 v[78:81], v[144:147], v[200:203], v[78:81]
	v_mfma_f32_16x16x32_bf16 v[70:73], v[152:155], v[200:203], v[70:73]
	v_mfma_f32_16x16x32_bf16 v[126:129], v[148:151], v[180:183], v[126:129]
	v_mfma_f32_16x16x32_bf16 v[118:121], v[156:159], v[180:183], v[118:121]
	v_mfma_f32_16x16x32_bf16 v[110:113], v[148:151], v[188:191], v[110:113]
	v_mfma_f32_16x16x32_bf16 v[102:105], v[156:159], v[188:191], v[102:105]
	v_mfma_f32_16x16x32_bf16 v[94:97], v[148:151], v[196:199], v[94:97]
	v_mfma_f32_16x16x32_bf16 v[86:89], v[156:159], v[196:199], v[86:89]
	v_mfma_f32_16x16x32_bf16 v[78:81], v[148:151], v[204:207], v[78:81]
	v_mfma_f32_16x16x32_bf16 v[70:73], v[156:159], v[204:207], v[70:73]
	s_setprio 0
	s_setprio 1
	v_mfma_f32_16x16x32_bf16 v[122:125], v[160:163], v[176:179], v[122:125]
	v_mfma_f32_16x16x32_bf16 v[114:117], v[168:171], v[176:179], v[114:117]
	v_mfma_f32_16x16x32_bf16 v[106:109], v[160:163], v[184:187], v[106:109]
	v_mfma_f32_16x16x32_bf16 v[98:101], v[168:171], v[184:187], v[98:101]
	v_mfma_f32_16x16x32_bf16 v[90:93], v[160:163], v[192:195], v[90:93]
	v_mfma_f32_16x16x32_bf16 v[82:85], v[168:171], v[192:195], v[82:85]
	v_mfma_f32_16x16x32_bf16 v[74:77], v[160:163], v[200:203], v[74:77]
	v_mfma_f32_16x16x32_bf16 v[66:69], v[168:171], v[200:203], v[66:69]
	v_mfma_f32_16x16x32_bf16 v[122:125], v[164:167], v[180:183], v[122:125]
	v_mfma_f32_16x16x32_bf16 v[114:117], v[172:175], v[180:183], v[114:117]
	v_mfma_f32_16x16x32_bf16 v[106:109], v[164:167], v[188:191], v[106:109]
	v_mfma_f32_16x16x32_bf16 v[98:101], v[172:175], v[188:191], v[98:101]
	v_mfma_f32_16x16x32_bf16 v[90:93], v[164:167], v[196:199], v[90:93]
	v_mfma_f32_16x16x32_bf16 v[82:85], v[172:175], v[196:199], v[82:85]
	v_mfma_f32_16x16x32_bf16 v[74:77], v[164:167], v[204:207], v[74:77]
	v_mfma_f32_16x16x32_bf16 v[66:69], v[172:175], v[204:207], v[66:69]
	s_setprio 0
	s_barrier
	s_add_i32 s48, s91, s37
	v_lshl_add_u64 v[216:217], v[216:217], 0, s[34:35]
	s_mov_b32 m0, s48
	ds_read_b128 v[176:179], v143 offset:49152
	ds_read_b128 v[180:183], v143 offset:50176
	ds_read_b128 v[184:187], v143 offset:51200
	ds_read_b128 v[188:191], v143 offset:52224
	ds_read_b128 v[192:195], v143 offset:53248
	ds_read_b128 v[196:199], v143 offset:54272
	ds_read_b128 v[200:203], v143 offset:55296
	ds_read_b128 v[204:207], v143 offset:56320
	global_load_lds_dwordx4 v[216:217], off
	s_add_i32 m0, s48, 0x2000
	s_add_u32 s28, s28, 0x80080
	v_lshl_add_u64 v[216:217], v[224:225], 0, s[34:35]
	s_addc_u32 s29, s29, 0
	s_add_i32 s48, s92, s37
	global_load_lds_dwordx4 v[216:217], off
	v_lshl_add_u64 v[216:217], s[28:29], 0, v[16:17]
	s_mov_b32 m0, s48
	s_nop 0
	global_load_lds_dwordx4 v[216:217], off
	v_lshl_add_u64 v[216:217], s[28:29], 0, v[130:131]
	s_add_i32 m0, s48, 0x2000
	s_nop 0
	global_load_lds_dwordx4 v[216:217], off
	v_lshl_add_u64 v[216:217], v[226:227], 0, s[34:35]
	s_mov_b32 m0, s59
	s_nop 0
	global_load_lds_dwordx4 v[216:217], off
	v_lshl_add_u64 v[216:217], v[228:229], 0, s[34:35]
	s_mov_b32 m0, s83
	s_nop 0
	global_load_lds_dwordx4 v[216:217], off
	s_waitcnt vmcnt(8)
	s_waitcnt lgkmcnt(0)
	s_barrier
	s_setprio 1
	s_waitcnt lgkmcnt(0)
	v_mfma_f32_16x16x32_bf16 v[62:65], v[144:147], v[176:179], v[62:65]
	v_mfma_f32_16x16x32_bf16 v[54:57], v[152:155], v[176:179], v[54:57]
	v_mfma_f32_16x16x32_bf16 v[46:49], v[144:147], v[184:187], v[46:49]
	v_mfma_f32_16x16x32_bf16 v[38:41], v[152:155], v[184:187], v[38:41]
	v_mfma_f32_16x16x32_bf16 v[30:33], v[144:147], v[192:195], v[30:33]
	v_mfma_f32_16x16x32_bf16 v[22:25], v[152:155], v[192:195], v[22:25]
	v_mfma_f32_16x16x32_bf16 v[12:15], v[144:147], v[200:203], v[12:15]
	v_mfma_f32_16x16x32_bf16 v[4:7], v[152:155], v[200:203], v[4:7]
	v_mfma_f32_16x16x32_bf16 v[62:65], v[148:151], v[180:183], v[62:65]
	v_mfma_f32_16x16x32_bf16 v[54:57], v[156:159], v[180:183], v[54:57]
	v_mfma_f32_16x16x32_bf16 v[46:49], v[148:151], v[188:191], v[46:49]
	v_mfma_f32_16x16x32_bf16 v[38:41], v[156:159], v[188:191], v[38:41]
	v_mfma_f32_16x16x32_bf16 v[30:33], v[148:151], v[196:199], v[30:33]
	v_mfma_f32_16x16x32_bf16 v[22:25], v[156:159], v[196:199], v[22:25]
	v_mfma_f32_16x16x32_bf16 v[12:15], v[148:151], v[204:207], v[12:15]
	v_mfma_f32_16x16x32_bf16 v[4:7], v[156:159], v[204:207], v[4:7]
	s_setprio 0
	s_setprio 1
	v_mfma_f32_16x16x32_bf16 v[58:61], v[160:163], v[176:179], v[58:61]
	v_mfma_f32_16x16x32_bf16 v[50:53], v[168:171], v[176:179], v[50:53]
	v_mfma_f32_16x16x32_bf16 v[42:45], v[160:163], v[184:187], v[42:45]
	v_mfma_f32_16x16x32_bf16 v[34:37], v[168:171], v[184:187], v[34:37]
	v_mfma_f32_16x16x32_bf16 v[26:29], v[160:163], v[192:195], v[26:29]
	v_mfma_f32_16x16x32_bf16 v[18:21], v[168:171], v[192:195], v[18:21]
	v_mfma_f32_16x16x32_bf16 v[8:11], v[160:163], v[200:203], v[8:11]
	v_mfma_f32_16x16x32_bf16 v[0:3], v[168:171], v[200:203], v[0:3]
	v_mfma_f32_16x16x32_bf16 v[58:61], v[164:167], v[180:183], v[58:61]
	v_mfma_f32_16x16x32_bf16 v[50:53], v[172:175], v[180:183], v[50:53]
	v_mfma_f32_16x16x32_bf16 v[42:45], v[164:167], v[188:191], v[42:45]
	v_mfma_f32_16x16x32_bf16 v[34:37], v[172:175], v[188:191], v[34:37]
	v_mfma_f32_16x16x32_bf16 v[26:29], v[164:167], v[196:199], v[26:29]
	v_mfma_f32_16x16x32_bf16 v[18:21], v[172:175], v[196:199], v[18:21]
	v_mfma_f32_16x16x32_bf16 v[8:11], v[164:167], v[204:207], v[8:11]
	v_mfma_f32_16x16x32_bf16 v[0:3], v[172:175], v[204:207], v[0:3]
	s_setprio 0
	s_barrier
	s_add_i32 s90, s90, 2
	s_add_u32 s46, s46, 0x100
	s_addc_u32 s47, s47, 0
	s_add_u32 s88, s88, 0x100
	s_addc_u32 s89, s89, 0
	s_cmp_gt_u32 s90, 29
	s_cbranch_scc1 .Lpk_I_exit

.LBB0_991:
	s_add_u32 s42, s42, 0x100
	v_mov_b32_e32 v0, 0
	s_addc_u32 s43, s43, 0
	s_mov_b32 s86, -2
	v_mov_b32_e32 v1, v0
	v_mov_b32_e32 v2, v0
	v_mov_b32_e32 v3, v0
	v_mov_b32_e32 v4, v0
	v_mov_b32_e32 v5, v0
	v_mov_b32_e32 v6, v0
	v_mov_b32_e32 v7, v0
	v_mov_b32_e32 v12, v0
	v_mov_b32_e32 v13, v0
	v_mov_b32_e32 v14, v0
	v_mov_b32_e32 v15, v0
	v_mov_b32_e32 v22, v0
	v_mov_b32_e32 v23, v0
	v_mov_b32_e32 v24, v0
	v_mov_b32_e32 v25, v0
	v_mov_b32_e32 v30, v0
	v_mov_b32_e32 v31, v0
	v_mov_b32_e32 v32, v0
	v_mov_b32_e32 v33, v0
	v_mov_b32_e32 v38, v0
	v_mov_b32_e32 v39, v0
	v_mov_b32_e32 v40, v0
	v_mov_b32_e32 v41, v0
	v_mov_b32_e32 v46, v0
	v_mov_b32_e32 v47, v0
	v_mov_b32_e32 v48, v0
	v_mov_b32_e32 v49, v0
	v_mov_b32_e32 v54, v0
	v_mov_b32_e32 v55, v0
	v_mov_b32_e32 v56, v0
	v_mov_b32_e32 v57, v0
	v_mov_b32_e32 v8, v0
	v_mov_b32_e32 v9, v0
	v_mov_b32_e32 v10, v0
	v_mov_b32_e32 v11, v0
	v_mov_b32_e32 v18, v0
	v_mov_b32_e32 v19, v0
	v_mov_b32_e32 v20, v0
	v_mov_b32_e32 v21, v0
	v_mov_b32_e32 v26, v0
	v_mov_b32_e32 v27, v0
	v_mov_b32_e32 v28, v0
	v_mov_b32_e32 v29, v0
	v_mov_b32_e32 v34, v0
	v_mov_b32_e32 v35, v0
	v_mov_b32_e32 v36, v0
	v_mov_b32_e32 v37, v0
	v_mov_b32_e32 v42, v0
	v_mov_b32_e32 v43, v0
	v_mov_b32_e32 v44, v0
	v_mov_b32_e32 v45, v0
	v_mov_b32_e32 v50, v0
	v_mov_b32_e32 v51, v0
	v_mov_b32_e32 v52, v0
	v_mov_b32_e32 v53, v0
	v_mov_b32_e32 v58, v0
	v_mov_b32_e32 v59, v0
	v_mov_b32_e32 v60, v0
	v_mov_b32_e32 v61, v0
	v_mov_b32_e32 v62, v0
	v_mov_b32_e32 v63, v0
	v_mov_b32_e32 v64, v0
	v_mov_b32_e32 v65, v0
	v_mov_b32_e32 v66, v0
	v_mov_b32_e32 v67, v0
	v_mov_b32_e32 v68, v0
	v_mov_b32_e32 v69, v0
	v_mov_b32_e32 v70, v0
	v_mov_b32_e32 v71, v0
	v_mov_b32_e32 v72, v0
	v_mov_b32_e32 v73, v0
	v_mov_b32_e32 v78, v0
	v_mov_b32_e32 v79, v0
	v_mov_b32_e32 v80, v0
	v_mov_b32_e32 v81, v0
	v_mov_b32_e32 v86, v0
	v_mov_b32_e32 v87, v0
	v_mov_b32_e32 v88, v0
	v_mov_b32_e32 v89, v0
	v_mov_b32_e32 v94, v0
	v_mov_b32_e32 v95, v0
	v_mov_b32_e32 v96, v0
	v_mov_b32_e32 v97, v0
	v_mov_b32_e32 v102, v0
	v_mov_b32_e32 v103, v0
	v_mov_b32_e32 v104, v0
	v_mov_b32_e32 v105, v0
	v_mov_b32_e32 v110, v0
	v_mov_b32_e32 v111, v0
	v_mov_b32_e32 v112, v0
	v_mov_b32_e32 v113, v0
	v_mov_b32_e32 v118, v0
	v_mov_b32_e32 v119, v0
	v_mov_b32_e32 v120, v0
	v_mov_b32_e32 v121, v0
	v_mov_b32_e32 v74, v0
	v_mov_b32_e32 v75, v0
	v_mov_b32_e32 v76, v0
	v_mov_b32_e32 v77, v0
	v_mov_b32_e32 v82, v0
	v_mov_b32_e32 v83, v0
	v_mov_b32_e32 v84, v0
	v_mov_b32_e32 v85, v0
	v_mov_b32_e32 v90, v0
	v_mov_b32_e32 v91, v0
	v_mov_b32_e32 v92, v0
	v_mov_b32_e32 v93, v0
	v_mov_b32_e32 v98, v0
	v_mov_b32_e32 v99, v0
	v_mov_b32_e32 v100, v0
	v_mov_b32_e32 v101, v0
	v_mov_b32_e32 v106, v0
	v_mov_b32_e32 v107, v0
	v_mov_b32_e32 v108, v0
	v_mov_b32_e32 v109, v0
	v_mov_b32_e32 v114, v0
	v_mov_b32_e32 v115, v0
	v_mov_b32_e32 v116, v0
	v_mov_b32_e32 v117, v0
	v_mov_b32_e32 v122, v0
	v_mov_b32_e32 v123, v0
	v_mov_b32_e32 v124, v0
	v_mov_b32_e32 v125, v0
	v_mov_b32_e32 v126, v0
	v_mov_b32_e32 v127, v0
	v_mov_b32_e32 v128, v0
	v_mov_b32_e32 v129, v0
	s_cmp_eq_u32 s58, 1
	s_cbranch_scc1 .LBB0_992
	s_add_u32 s36, s26, 0x100
	s_addc_u32 s37, s27, 0
	s_add_i32 s87, 0, 0x10000
	s_cmpk_eq_i32 s86, 0x54
	s_cselect_b32 s41, s19, s37
	s_cselect_b32 s40, s18, s36
	s_cselect_b32 s29, s23, s43
	s_cselect_b32 s28, s22, s42
	s_add_i32 s88, 0, 0x14000
	v_add_u32_e32 v142, s87, v203
	v_add_u32_e32 v158, s88, v203
	ds_read_b128 v[130:133], v142
	ds_read_b128 v[134:137], v142 offset:1024
	ds_read_b128 v[138:141], v142 offset:2048
	ds_read_b128 v[142:145], v142 offset:3072
	ds_read_b128 v[146:149], v158
	ds_read_b128 v[150:153], v158 offset:1024
	ds_read_b128 v[154:157], v158 offset:2048
	ds_read_b128 v[158:161], v158 offset:3072
	v_lshl_add_u64 v[200:201], s[26:27], 0, v[188:189]
	s_add_i32 m0, s47, 0xc000
	ds_read_b128 v[162:165], v205
	ds_read_b128 v[166:169], v205 offset:1024
	ds_read_b128 v[170:173], v205 offset:2048
	ds_read_b128 v[174:177], v205 offset:3072
	ds_read_b128 v[178:181], v205 offset:4096
	ds_read_b128 v[192:195], v205 offset:5120
	ds_read_b128 v[196:199], v205 offset:6144
	ds_read_b128 v[224:227], v205 offset:7168
	global_load_lds_dwordx4 v[200:201], off
	v_lshl_add_u64 v[200:201], s[26:27], 0, v[190:191]
	s_add_i32 m0, s47, 0xe000
	s_nop 0
	global_load_lds_dwordx4 v[200:201], off
	s_waitcnt vmcnt(24)
	s_waitcnt lgkmcnt(0)
	s_barrier
	s_setprio 1
	s_waitcnt lgkmcnt(0)
	v_mfma_f32_16x16x32_bf16 v[126:129], v[130:133], v[162:165], v[126:129]
	v_mfma_f32_16x16x32_bf16 v[122:125], v[138:141], v[162:165], v[122:125]
	v_mfma_f32_16x16x32_bf16 v[114:117], v[130:133], v[170:173], v[114:117]
	v_mfma_f32_16x16x32_bf16 v[106:109], v[138:141], v[170:173], v[106:109]
	v_mfma_f32_16x16x32_bf16 v[98:101], v[130:133], v[178:181], v[98:101]
	v_mfma_f32_16x16x32_bf16 v[90:93], v[138:141], v[178:181], v[90:93]
	v_mfma_f32_16x16x32_bf16 v[82:85], v[130:133], v[196:199], v[82:85]
	v_mfma_f32_16x16x32_bf16 v[74:77], v[138:141], v[196:199], v[74:77]
	v_mfma_f32_16x16x32_bf16 v[126:129], v[134:137], v[166:169], v[126:129]
	v_mfma_f32_16x16x32_bf16 v[122:125], v[142:145], v[166:169], v[122:125]
	v_mfma_f32_16x16x32_bf16 v[114:117], v[134:137], v[174:177], v[114:117]
	v_mfma_f32_16x16x32_bf16 v[106:109], v[142:145], v[174:177], v[106:109]
	v_mfma_f32_16x16x32_bf16 v[98:101], v[134:137], v[192:195], v[98:101]
	v_mfma_f32_16x16x32_bf16 v[90:93], v[142:145], v[192:195], v[90:93]
	v_mfma_f32_16x16x32_bf16 v[82:85], v[134:137], v[224:227], v[82:85]
	v_mfma_f32_16x16x32_bf16 v[74:77], v[142:145], v[224:227], v[74:77]
	s_setprio 0
	s_setprio 1
	v_mfma_f32_16x16x32_bf16 v[118:121], v[146:149], v[162:165], v[118:121]
	v_mfma_f32_16x16x32_bf16 v[110:113], v[154:157], v[162:165], v[110:113]
	v_mfma_f32_16x16x32_bf16 v[102:105], v[146:149], v[170:173], v[102:105]
	v_mfma_f32_16x16x32_bf16 v[94:97], v[154:157], v[170:173], v[94:97]
	v_mfma_f32_16x16x32_bf16 v[86:89], v[146:149], v[178:181], v[86:89]
	v_mfma_f32_16x16x32_bf16 v[78:81], v[154:157], v[178:181], v[78:81]
	v_mfma_f32_16x16x32_bf16 v[70:73], v[146:149], v[196:199], v[70:73]
	v_mfma_f32_16x16x32_bf16 v[66:69], v[154:157], v[196:199], v[66:69]
	v_mfma_f32_16x16x32_bf16 v[118:121], v[150:153], v[166:169], v[118:121]
	v_mfma_f32_16x16x32_bf16 v[110:113], v[158:161], v[166:169], v[110:113]
	v_mfma_f32_16x16x32_bf16 v[102:105], v[150:153], v[174:177], v[102:105]
	v_mfma_f32_16x16x32_bf16 v[94:97], v[158:161], v[174:177], v[94:97]
	v_mfma_f32_16x16x32_bf16 v[86:89], v[150:153], v[192:195], v[86:89]
	v_mfma_f32_16x16x32_bf16 v[78:81], v[158:161], v[192:195], v[78:81]
	v_mfma_f32_16x16x32_bf16 v[70:73], v[150:153], v[224:227], v[70:73]
	v_mfma_f32_16x16x32_bf16 v[66:69], v[158:161], v[224:227], v[66:69]
	s_setprio 0
	s_barrier
	s_add_i32 s26, s87, s45
	v_lshl_add_u64 v[200:201], s[28:29], 0, v[16:17]
	s_mov_b32 m0, s26
	ds_read_b128 v[162:165], v205 offset:16384
	ds_read_b128 v[166:169], v205 offset:17408
	ds_read_b128 v[170:173], v205 offset:18432
	ds_read_b128 v[174:177], v205 offset:19456
	ds_read_b128 v[178:181], v205 offset:20480
	ds_read_b128 v[192:195], v205 offset:21504
	ds_read_b128 v[196:199], v205 offset:22528
	ds_read_b128 v[224:227], v205 offset:23552
	global_load_lds_dwordx4 v[200:201], off
	s_add_i32 m0, s26, 0x2000
	s_add_u32 s26, s28, 0x160000
	v_lshl_add_u64 v[206:207], s[28:29], 0, v[182:183]
	s_addc_u32 s27, s29, 0
	s_add_i32 s87, s88, s45
	global_load_lds_dwordx4 v[206:207], off
	v_lshl_add_u64 v[216:217], s[26:27], 0, v[16:17]
	s_mov_b32 m0, s87
	v_lshl_add_u64 v[228:229], s[40:41], 0, v[184:185]
	global_load_lds_dwordx4 v[216:217], off
	v_lshl_add_u64 v[216:217], s[26:27], 0, v[182:183]
	s_add_i32 m0, s87, 0x2000
	s_nop 0
	global_load_lds_dwordx4 v[216:217], off
	v_lshl_add_u64 v[216:217], s[40:41], 0, v[186:187]
	s_mov_b32 m0, s47
	s_nop 0
	global_load_lds_dwordx4 v[216:217], off
	s_mov_b32 m0, s48
	s_nop 0
	global_load_lds_dwordx4 v[228:229], off
	s_waitcnt vmcnt(24)
	s_waitcnt lgkmcnt(0)
	s_barrier
	s_setprio 1
	s_waitcnt lgkmcnt(0)
	v_mfma_f32_16x16x32_bf16 v[62:65], v[130:133], v[162:165], v[62:65]
	v_mfma_f32_16x16x32_bf16 v[58:61], v[138:141], v[162:165], v[58:61]
	v_mfma_f32_16x16x32_bf16 v[50:53], v[130:133], v[170:173], v[50:53]
	v_mfma_f32_16x16x32_bf16 v[42:45], v[138:141], v[170:173], v[42:45]
	v_mfma_f32_16x16x32_bf16 v[34:37], v[130:133], v[178:181], v[34:37]
	v_mfma_f32_16x16x32_bf16 v[26:29], v[138:141], v[178:181], v[26:29]
	v_mfma_f32_16x16x32_bf16 v[18:21], v[130:133], v[196:199], v[18:21]
	v_mfma_f32_16x16x32_bf16 v[8:11], v[138:141], v[196:199], v[8:11]
	v_mfma_f32_16x16x32_bf16 v[62:65], v[134:137], v[166:169], v[62:65]
	v_mfma_f32_16x16x32_bf16 v[58:61], v[142:145], v[166:169], v[58:61]
	v_mfma_f32_16x16x32_bf16 v[50:53], v[134:137], v[174:177], v[50:53]
	v_mfma_f32_16x16x32_bf16 v[42:45], v[142:145], v[174:177], v[42:45]
	v_mfma_f32_16x16x32_bf16 v[34:37], v[134:137], v[192:195], v[34:37]
	v_mfma_f32_16x16x32_bf16 v[26:29], v[142:145], v[192:195], v[26:29]
	v_mfma_f32_16x16x32_bf16 v[18:21], v[134:137], v[224:227], v[18:21]
	v_mfma_f32_16x16x32_bf16 v[8:11], v[142:145], v[224:227], v[8:11]
	s_setprio 0
	s_setprio 1
	v_mfma_f32_16x16x32_bf16 v[54:57], v[146:149], v[162:165], v[54:57]
	v_mfma_f32_16x16x32_bf16 v[46:49], v[154:157], v[162:165], v[46:49]
	v_mfma_f32_16x16x32_bf16 v[38:41], v[146:149], v[170:173], v[38:41]
	v_mfma_f32_16x16x32_bf16 v[30:33], v[154:157], v[170:173], v[30:33]
	v_mfma_f32_16x16x32_bf16 v[22:25], v[146:149], v[178:181], v[22:25]
	v_mfma_f32_16x16x32_bf16 v[12:15], v[154:157], v[178:181], v[12:15]
	v_mfma_f32_16x16x32_bf16 v[4:7], v[146:149], v[196:199], v[4:7]
	v_mfma_f32_16x16x32_bf16 v[0:3], v[154:157], v[196:199], v[0:3]
	v_mfma_f32_16x16x32_bf16 v[54:57], v[150:153], v[166:169], v[54:57]
	v_mfma_f32_16x16x32_bf16 v[46:49], v[158:161], v[166:169], v[46:49]
	v_mfma_f32_16x16x32_bf16 v[38:41], v[150:153], v[174:177], v[38:41]
	v_mfma_f32_16x16x32_bf16 v[30:33], v[158:161], v[174:177], v[30:33]
	v_mfma_f32_16x16x32_bf16 v[22:25], v[150:153], v[192:195], v[22:25]
	v_mfma_f32_16x16x32_bf16 v[12:15], v[158:161], v[192:195], v[12:15]
	v_mfma_f32_16x16x32_bf16 v[4:7], v[150:153], v[224:227], v[4:7]
	v_mfma_f32_16x16x32_bf16 v[0:3], v[158:161], v[224:227], v[0:3]
	s_setprio 0
	s_barrier
	s_add_i32 s87, 0, 0x18000
	s_add_i32 s88, 0, 0x1c000
	v_add_u32_e32 v142, s87, v203
	v_add_u32_e32 v158, s88, v203
	ds_read_b128 v[130:133], v142
	ds_read_b128 v[134:137], v142 offset:1024
	ds_read_b128 v[138:141], v142 offset:2048
	ds_read_b128 v[142:145], v142 offset:3072
	ds_read_b128 v[146:149], v158
	ds_read_b128 v[150:153], v158 offset:1024
	ds_read_b128 v[154:157], v158 offset:2048
	ds_read_b128 v[158:161], v158 offset:3072
	s_add_u32 s26, s40, 0x160000
	s_addc_u32 s27, s41, 0
	s_mov_b32 m0, s49
	v_lshl_add_u64 v[230:231], s[26:27], 0, v[186:187]
	ds_read_b128 v[162:165], v205 offset:32768
	ds_read_b128 v[166:169], v205 offset:33792
	ds_read_b128 v[170:173], v205 offset:34816
	ds_read_b128 v[174:177], v205 offset:35840
	ds_read_b128 v[178:181], v205 offset:36864
	ds_read_b128 v[192:195], v205 offset:37888
	ds_read_b128 v[196:199], v205 offset:38912
	ds_read_b128 v[224:227], v205 offset:39936
	global_load_lds_dwordx4 v[230:231], off
	v_lshl_add_u64 v[230:231], s[26:27], 0, v[184:185]
	s_mov_b32 m0, s50
	s_nop 0
	global_load_lds_dwordx4 v[230:231], off
	s_waitcnt vmcnt(8)
	s_waitcnt lgkmcnt(0)
	s_barrier
	s_setprio 1
	s_waitcnt lgkmcnt(0)
	v_mfma_f32_16x16x32_bf16 v[126:129], v[130:133], v[162:165], v[126:129]
	v_mfma_f32_16x16x32_bf16 v[122:125], v[138:141], v[162:165], v[122:125]
	v_mfma_f32_16x16x32_bf16 v[114:117], v[130:133], v[170:173], v[114:117]
	v_mfma_f32_16x16x32_bf16 v[106:109], v[138:141], v[170:173], v[106:109]
	v_mfma_f32_16x16x32_bf16 v[98:101], v[130:133], v[178:181], v[98:101]
	v_mfma_f32_16x16x32_bf16 v[90:93], v[138:141], v[178:181], v[90:93]
	v_mfma_f32_16x16x32_bf16 v[82:85], v[130:133], v[196:199], v[82:85]
	v_mfma_f32_16x16x32_bf16 v[74:77], v[138:141], v[196:199], v[74:77]
	v_mfma_f32_16x16x32_bf16 v[126:129], v[134:137], v[166:169], v[126:129]
	v_mfma_f32_16x16x32_bf16 v[122:125], v[142:145], v[166:169], v[122:125]
	v_mfma_f32_16x16x32_bf16 v[114:117], v[134:137], v[174:177], v[114:117]
	v_mfma_f32_16x16x32_bf16 v[106:109], v[142:145], v[174:177], v[106:109]
	v_mfma_f32_16x16x32_bf16 v[98:101], v[134:137], v[192:195], v[98:101]
	v_mfma_f32_16x16x32_bf16 v[90:93], v[142:145], v[192:195], v[90:93]
	v_mfma_f32_16x16x32_bf16 v[82:85], v[134:137], v[224:227], v[82:85]
	v_mfma_f32_16x16x32_bf16 v[74:77], v[142:145], v[224:227], v[74:77]
	s_setprio 0
	s_setprio 1
	v_mfma_f32_16x16x32_bf16 v[118:121], v[146:149], v[162:165], v[118:121]
	v_mfma_f32_16x16x32_bf16 v[110:113], v[154:157], v[162:165], v[110:113]
	v_mfma_f32_16x16x32_bf16 v[102:105], v[146:149], v[170:173], v[102:105]
	v_mfma_f32_16x16x32_bf16 v[94:97], v[154:157], v[170:173], v[94:97]
	v_mfma_f32_16x16x32_bf16 v[86:89], v[146:149], v[178:181], v[86:89]
	v_mfma_f32_16x16x32_bf16 v[78:81], v[154:157], v[178:181], v[78:81]
	v_mfma_f32_16x16x32_bf16 v[70:73], v[146:149], v[196:199], v[70:73]
	v_mfma_f32_16x16x32_bf16 v[66:69], v[154:157], v[196:199], v[66:69]
	v_mfma_f32_16x16x32_bf16 v[118:121], v[150:153], v[166:169], v[118:121]
	v_mfma_f32_16x16x32_bf16 v[110:113], v[158:161], v[166:169], v[110:113]
	v_mfma_f32_16x16x32_bf16 v[102:105], v[150:153], v[174:177], v[102:105]
	v_mfma_f32_16x16x32_bf16 v[94:97], v[158:161], v[174:177], v[94:97]
	v_mfma_f32_16x16x32_bf16 v[86:89], v[150:153], v[192:195], v[86:89]
	v_mfma_f32_16x16x32_bf16 v[78:81], v[158:161], v[192:195], v[78:81]
	v_mfma_f32_16x16x32_bf16 v[70:73], v[150:153], v[224:227], v[70:73]
	v_mfma_f32_16x16x32_bf16 v[66:69], v[158:161], v[224:227], v[66:69]
	s_setprio 0
	s_barrier
	s_add_i32 s26, s87, s45
	v_lshl_add_u64 v[200:201], v[200:201], 0, s[34:35]
	s_mov_b32 m0, s26
	ds_read_b128 v[162:165], v205 offset:49152
	ds_read_b128 v[166:169], v205 offset:50176
	ds_read_b128 v[170:173], v205 offset:51200
	ds_read_b128 v[174:177], v205 offset:52224
	ds_read_b128 v[178:181], v205 offset:53248
	ds_read_b128 v[192:195], v205 offset:54272
	ds_read_b128 v[196:199], v205 offset:55296
	ds_read_b128 v[224:227], v205 offset:56320
	global_load_lds_dwordx4 v[200:201], off
	s_add_i32 m0, s26, 0x2000
	s_add_u32 s26, s28, 0x160080
	v_lshl_add_u64 v[200:201], v[206:207], 0, s[34:35]
	s_addc_u32 s27, s29, 0
	s_add_i32 s28, s88, s45
	global_load_lds_dwordx4 v[200:201], off
	v_lshl_add_u64 v[200:201], s[26:27], 0, v[16:17]
	s_mov_b32 m0, s28
	s_nop 0
	global_load_lds_dwordx4 v[200:201], off
	v_lshl_add_u64 v[200:201], s[26:27], 0, v[182:183]
	s_add_i32 m0, s28, 0x2000
	s_nop 0
	global_load_lds_dwordx4 v[200:201], off
	v_lshl_add_u64 v[200:201], v[216:217], 0, s[34:35]
	s_mov_b32 m0, s53
	s_nop 0
	global_load_lds_dwordx4 v[200:201], off
	v_lshl_add_u64 v[200:201], v[228:229], 0, s[34:35]
	s_mov_b32 m0, s57
	s_nop 0
	global_load_lds_dwordx4 v[200:201], off
	s_waitcnt vmcnt(8)
	s_waitcnt lgkmcnt(0)
	s_barrier
	s_setprio 1
	s_waitcnt lgkmcnt(0)
	v_mfma_f32_16x16x32_bf16 v[62:65], v[130:133], v[162:165], v[62:65]
	v_mfma_f32_16x16x32_bf16 v[58:61], v[138:141], v[162:165], v[58:61]
	v_mfma_f32_16x16x32_bf16 v[50:53], v[130:133], v[170:173], v[50:53]
	v_mfma_f32_16x16x32_bf16 v[42:45], v[138:141], v[170:173], v[42:45]
	v_mfma_f32_16x16x32_bf16 v[34:37], v[130:133], v[178:181], v[34:37]
	v_mfma_f32_16x16x32_bf16 v[26:29], v[138:141], v[178:181], v[26:29]
	v_mfma_f32_16x16x32_bf16 v[18:21], v[130:133], v[196:199], v[18:21]
	v_mfma_f32_16x16x32_bf16 v[8:11], v[138:141], v[196:199], v[8:11]
	v_mfma_f32_16x16x32_bf16 v[62:65], v[134:137], v[166:169], v[62:65]
	v_mfma_f32_16x16x32_bf16 v[58:61], v[142:145], v[166:169], v[58:61]
	v_mfma_f32_16x16x32_bf16 v[50:53], v[134:137], v[174:177], v[50:53]
	v_mfma_f32_16x16x32_bf16 v[42:45], v[142:145], v[174:177], v[42:45]
	v_mfma_f32_16x16x32_bf16 v[34:37], v[134:137], v[192:195], v[34:37]
	v_mfma_f32_16x16x32_bf16 v[26:29], v[142:145], v[192:195], v[26:29]
	v_mfma_f32_16x16x32_bf16 v[18:21], v[134:137], v[224:227], v[18:21]
	v_mfma_f32_16x16x32_bf16 v[8:11], v[142:145], v[224:227], v[8:11]
	s_setprio 0
	s_setprio 1
	v_mfma_f32_16x16x32_bf16 v[54:57], v[146:149], v[162:165], v[54:57]
	v_mfma_f32_16x16x32_bf16 v[46:49], v[154:157], v[162:165], v[46:49]
	v_mfma_f32_16x16x32_bf16 v[38:41], v[146:149], v[170:173], v[38:41]
	v_mfma_f32_16x16x32_bf16 v[30:33], v[154:157], v[170:173], v[30:33]
	v_mfma_f32_16x16x32_bf16 v[22:25], v[146:149], v[178:181], v[22:25]
	v_mfma_f32_16x16x32_bf16 v[12:15], v[154:157], v[178:181], v[12:15]
	v_mfma_f32_16x16x32_bf16 v[4:7], v[146:149], v[196:199], v[4:7]
	v_mfma_f32_16x16x32_bf16 v[0:3], v[154:157], v[196:199], v[0:3]
	v_mfma_f32_16x16x32_bf16 v[54:57], v[150:153], v[166:169], v[54:57]
	v_mfma_f32_16x16x32_bf16 v[46:49], v[158:161], v[166:169], v[46:49]
	v_mfma_f32_16x16x32_bf16 v[38:41], v[150:153], v[174:177], v[38:41]
	v_mfma_f32_16x16x32_bf16 v[30:33], v[158:161], v[174:177], v[30:33]
	v_mfma_f32_16x16x32_bf16 v[22:25], v[150:153], v[192:195], v[22:25]
	v_mfma_f32_16x16x32_bf16 v[12:15], v[158:161], v[192:195], v[12:15]
	v_mfma_f32_16x16x32_bf16 v[4:7], v[150:153], v[224:227], v[4:7]
	v_mfma_f32_16x16x32_bf16 v[0:3], v[158:161], v[224:227], v[0:3]
	s_setprio 0
	s_barrier
	s_add_i32 s86, s86, 2
	s_add_u32 s42, s42, 0x100
	s_addc_u32 s43, s43, 0
	s_cmpk_gt_u32 s86, 0x55
	s_mov_b64 s[26:27], s[36:37]
	s_cbranch_scc1 .Lpk_J_exit
